# P0 fnet mixing matrix: 128 broadcast weight loads per output issued up front; cos or sin chosen per wave
# speedup vs baseline: 1.0106x; 1.0047x over previous
.LBB0_96:
	v_lshrrev_b32_e32 v6, 5, v0
	v_lshlrev_b32_e32 v4, 1, v0
	v_and_b32_e32 v6, 0x1fc, v6
	v_and_or_b32 v4, v4, s30, v6
	s_waitcnt lgkmcnt(0)
	v_lshl_add_u64 v[6:7], s[8:9], 0, v[4:5]
	v_and_b32_e32 v4, 0x4000, v0
	v_cmp_eq_u32_e32 vcc, 0, v4
	s_mov_b64 s[14:15], 0
	v_mov_b32_e32 v15, 0
	v_mov_b32_e32 v4, 0
	s_mov_b32 s14, 0x1000
	s_mov_b32 s15, 0
	v_mov_b32_e32 v16, v6
	v_mov_b32_e32 v17, v7
	global_load_dword v84, v[16:17], off
	global_load_dword v85, v[16:17], off offset:512
	global_load_dword v86, v[16:17], off offset:1024
	global_load_dword v87, v[16:17], off offset:1536
	global_load_dword v88, v[16:17], off offset:2048
	global_load_dword v89, v[16:17], off offset:2560
	global_load_dword v90, v[16:17], off offset:3072
	global_load_dword v91, v[16:17], off offset:3584
	v_lshl_add_u64 v[16:17], v[16:17], 0, s[14:15]
	global_load_dword v92, v[16:17], off
	global_load_dword v93, v[16:17], off offset:512
	global_load_dword v94, v[16:17], off offset:1024
	global_load_dword v95, v[16:17], off offset:1536
	global_load_dword v96, v[16:17], off offset:2048
	global_load_dword v97, v[16:17], off offset:2560
	global_load_dword v98, v[16:17], off offset:3072
	global_load_dword v99, v[16:17], off offset:3584
	v_lshl_add_u64 v[16:17], v[16:17], 0, s[14:15]
	global_load_dword v100, v[16:17], off
	global_load_dword v101, v[16:17], off offset:512
	global_load_dword v102, v[16:17], off offset:1024
	global_load_dword v103, v[16:17], off offset:1536
	global_load_dword v104, v[16:17], off offset:2048
	global_load_dword v105, v[16:17], off offset:2560
	global_load_dword v106, v[16:17], off offset:3072
	global_load_dword v107, v[16:17], off offset:3584
	v_lshl_add_u64 v[16:17], v[16:17], 0, s[14:15]
	global_load_dword v108, v[16:17], off
	global_load_dword v109, v[16:17], off offset:512
	global_load_dword v110, v[16:17], off offset:1024
	global_load_dword v111, v[16:17], off offset:1536
	global_load_dword v112, v[16:17], off offset:2048
	global_load_dword v113, v[16:17], off offset:2560
	global_load_dword v114, v[16:17], off offset:3072
	global_load_dword v115, v[16:17], off offset:3584
	v_lshl_add_u64 v[16:17], v[16:17], 0, s[14:15]
	global_load_dword v116, v[16:17], off
	global_load_dword v117, v[16:17], off offset:512
	global_load_dword v118, v[16:17], off offset:1024
	global_load_dword v119, v[16:17], off offset:1536
	global_load_dword v120, v[16:17], off offset:2048
	global_load_dword v121, v[16:17], off offset:2560
	global_load_dword v122, v[16:17], off offset:3072
	global_load_dword v123, v[16:17], off offset:3584
	v_lshl_add_u64 v[16:17], v[16:17], 0, s[14:15]
	global_load_dword v124, v[16:17], off
	global_load_dword v125, v[16:17], off offset:512
	global_load_dword v126, v[16:17], off offset:1024
	global_load_dword v127, v[16:17], off offset:1536
	global_load_dword v128, v[16:17], off offset:2048
	global_load_dword v129, v[16:17], off offset:2560
	global_load_dword v130, v[16:17], off offset:3072
	global_load_dword v131, v[16:17], off offset:3584
	v_lshl_add_u64 v[16:17], v[16:17], 0, s[14:15]
	global_load_dword v132, v[16:17], off
	global_load_dword v133, v[16:17], off offset:512
	global_load_dword v134, v[16:17], off offset:1024
	global_load_dword v135, v[16:17], off offset:1536
	global_load_dword v136, v[16:17], off offset:2048
	global_load_dword v137, v[16:17], off offset:2560
	global_load_dword v138, v[16:17], off offset:3072
	global_load_dword v139, v[16:17], off offset:3584
	v_lshl_add_u64 v[16:17], v[16:17], 0, s[14:15]
	global_load_dword v140, v[16:17], off
	global_load_dword v141, v[16:17], off offset:512
	global_load_dword v142, v[16:17], off offset:1024
	global_load_dword v143, v[16:17], off offset:1536
	global_load_dword v144, v[16:17], off offset:2048
	global_load_dword v145, v[16:17], off offset:2560
	global_load_dword v146, v[16:17], off offset:3072
	global_load_dword v147, v[16:17], off offset:3584
	v_lshl_add_u64 v[16:17], v[16:17], 0, s[14:15]
	global_load_dword v148, v[16:17], off
	global_load_dword v149, v[16:17], off offset:512
	global_load_dword v150, v[16:17], off offset:1024
	global_load_dword v151, v[16:17], off offset:1536
	global_load_dword v152, v[16:17], off offset:2048
	global_load_dword v153, v[16:17], off offset:2560
	global_load_dword v154, v[16:17], off offset:3072
	global_load_dword v155, v[16:17], off offset:3584
	v_lshl_add_u64 v[16:17], v[16:17], 0, s[14:15]
	global_load_dword v156, v[16:17], off
	global_load_dword v157, v[16:17], off offset:512
	global_load_dword v158, v[16:17], off offset:1024
	global_load_dword v159, v[16:17], off offset:1536
	global_load_dword v160, v[16:17], off offset:2048
	global_load_dword v161, v[16:17], off offset:2560
	global_load_dword v162, v[16:17], off offset:3072
	global_load_dword v163, v[16:17], off offset:3584
	v_lshl_add_u64 v[16:17], v[16:17], 0, s[14:15]
	global_load_dword v164, v[16:17], off
	global_load_dword v165, v[16:17], off offset:512
	global_load_dword v166, v[16:17], off offset:1024
	global_load_dword v167, v[16:17], off offset:1536
	global_load_dword v168, v[16:17], off offset:2048
	global_load_dword v169, v[16:17], off offset:2560
	global_load_dword v170, v[16:17], off offset:3072
	global_load_dword v171, v[16:17], off offset:3584
	v_lshl_add_u64 v[16:17], v[16:17], 0, s[14:15]
	global_load_dword v172, v[16:17], off
	global_load_dword v173, v[16:17], off offset:512
	global_load_dword v174, v[16:17], off offset:1024
	global_load_dword v175, v[16:17], off offset:1536
	global_load_dword v178, v[16:17], off offset:2048
	global_load_dword v179, v[16:17], off offset:2560
	global_load_dword v180, v[16:17], off offset:3072
	global_load_dword v181, v[16:17], off offset:3584
	v_lshl_add_u64 v[16:17], v[16:17], 0, s[14:15]
	global_load_dword v182, v[16:17], off
	global_load_dword v183, v[16:17], off offset:512
	global_load_dword v184, v[16:17], off offset:1024
	global_load_dword v185, v[16:17], off offset:1536
	global_load_dword v186, v[16:17], off offset:2048
	global_load_dword v187, v[16:17], off offset:2560
	global_load_dword v188, v[16:17], off offset:3072
	global_load_dword v189, v[16:17], off offset:3584
	v_lshl_add_u64 v[16:17], v[16:17], 0, s[14:15]
	global_load_dword v190, v[16:17], off
	global_load_dword v191, v[16:17], off offset:512
	global_load_dword v192, v[16:17], off offset:1024
	global_load_dword v193, v[16:17], off offset:1536
	global_load_dword v194, v[16:17], off offset:2048
	global_load_dword v195, v[16:17], off offset:2560
	global_load_dword v196, v[16:17], off offset:3072
	global_load_dword v197, v[16:17], off offset:3584
	v_lshl_add_u64 v[16:17], v[16:17], 0, s[14:15]
	global_load_dword v198, v[16:17], off
	global_load_dword v199, v[16:17], off offset:512
	global_load_dword v200, v[16:17], off offset:1024
	global_load_dword v201, v[16:17], off offset:1536
	global_load_dword v202, v[16:17], off offset:2048
	global_load_dword v203, v[16:17], off offset:2560
	global_load_dword v204, v[16:17], off offset:3072
	global_load_dword v205, v[16:17], off offset:3584
	v_lshl_add_u64 v[16:17], v[16:17], 0, s[14:15]
	global_load_dword v206, v[16:17], off
	global_load_dword v207, v[16:17], off offset:512
	global_load_dword v208, v[16:17], off offset:1024
	global_load_dword v209, v[16:17], off offset:1536
	global_load_dword v210, v[16:17], off offset:2048
	global_load_dword v211, v[16:17], off offset:2560
	global_load_dword v212, v[16:17], off offset:3072
	global_load_dword v213, v[16:17], off offset:3584
	v_and_b32_e32 v18, 0x7f, v0
	v_mov_b32_e32 v19, 0
	s_and_b64 s[14:15], vcc, exec
	s_cbranch_scc0 .Lmc_sin
	v_cvt_f32_ubyte0_e32 v20, v19
	v_add_u32_e32 v19, v19, v18
	v_mul_f32_e32 v20, 0x3d490fdb, v20
	v_and_b32_e32 v19, 0x7f, v19
	v_mul_f32_e32 v20, 0.15915494, v20
	v_cos_f32_e32 v20, v20
	v_cvt_f32_ubyte0_e32 v21, v19
	v_add_u32_e32 v19, v19, v18
	v_mul_f32_e32 v21, 0x3d490fdb, v21
	v_and_b32_e32 v19, 0x7f, v19
	v_mul_f32_e32 v21, 0.15915494, v21
	v_cos_f32_e32 v21, v21
	v_cvt_f32_ubyte0_e32 v22, v19
	v_add_u32_e32 v19, v19, v18
	v_mul_f32_e32 v22, 0x3d490fdb, v22
	v_and_b32_e32 v19, 0x7f, v19
	v_mul_f32_e32 v22, 0.15915494, v22
	v_cos_f32_e32 v22, v22
	s_waitcnt vmcnt(63)
	v_fmac_f32_e32 v4, v84, v20
	v_cvt_f32_ubyte0_e32 v23, v19
	v_add_u32_e32 v19, v19, v18
	v_mul_f32_e32 v23, 0x3d490fdb, v23
	v_and_b32_e32 v19, 0x7f, v19
	v_mul_f32_e32 v23, 0.15915494, v23
	v_cos_f32_e32 v23, v23
	v_fmac_f32_e32 v4, v85, v21
	v_cvt_f32_ubyte0_e32 v20, v19
	v_add_u32_e32 v19, v19, v18
	v_mul_f32_e32 v20, 0x3d490fdb, v20
	v_and_b32_e32 v19, 0x7f, v19
	v_mul_f32_e32 v20, 0.15915494, v20
	v_cos_f32_e32 v20, v20
	v_fmac_f32_e32 v4, v86, v22
	v_cvt_f32_ubyte0_e32 v21, v19
	v_add_u32_e32 v19, v19, v18
	v_mul_f32_e32 v21, 0x3d490fdb, v21
	v_and_b32_e32 v19, 0x7f, v19
	v_mul_f32_e32 v21, 0.15915494, v21
	v_cos_f32_e32 v21, v21
	v_fmac_f32_e32 v4, v87, v23
	v_cvt_f32_ubyte0_e32 v22, v19
	v_add_u32_e32 v19, v19, v18
	v_mul_f32_e32 v22, 0x3d490fdb, v22
	v_and_b32_e32 v19, 0x7f, v19
	v_mul_f32_e32 v22, 0.15915494, v22
	v_cos_f32_e32 v22, v22
	v_fmac_f32_e32 v4, v88, v20
	v_cvt_f32_ubyte0_e32 v23, v19
	v_add_u32_e32 v19, v19, v18
	v_mul_f32_e32 v23, 0x3d490fdb, v23
	v_and_b32_e32 v19, 0x7f, v19
	v_mul_f32_e32 v23, 0.15915494, v23
	v_cos_f32_e32 v23, v23
	v_fmac_f32_e32 v4, v89, v21
	v_cvt_f32_ubyte0_e32 v20, v19
	v_add_u32_e32 v19, v19, v18
	v_mul_f32_e32 v20, 0x3d490fdb, v20
	v_and_b32_e32 v19, 0x7f, v19
	v_mul_f32_e32 v20, 0.15915494, v20
	v_cos_f32_e32 v20, v20
	v_fmac_f32_e32 v4, v90, v22
	v_cvt_f32_ubyte0_e32 v21, v19
	v_add_u32_e32 v19, v19, v18
	v_mul_f32_e32 v21, 0x3d490fdb, v21
	v_and_b32_e32 v19, 0x7f, v19
	v_mul_f32_e32 v21, 0.15915494, v21
	v_cos_f32_e32 v21, v21
	v_fmac_f32_e32 v4, v91, v23
	v_cvt_f32_ubyte0_e32 v22, v19
	v_add_u32_e32 v19, v19, v18
	v_mul_f32_e32 v22, 0x3d490fdb, v22
	v_and_b32_e32 v19, 0x7f, v19
	v_mul_f32_e32 v22, 0.15915494, v22
	v_cos_f32_e32 v22, v22
	v_fmac_f32_e32 v4, v92, v20
	v_cvt_f32_ubyte0_e32 v23, v19
	v_add_u32_e32 v19, v19, v18
	v_mul_f32_e32 v23, 0x3d490fdb, v23
	v_and_b32_e32 v19, 0x7f, v19
	v_mul_f32_e32 v23, 0.15915494, v23
	v_cos_f32_e32 v23, v23
	v_fmac_f32_e32 v4, v93, v21
	v_cvt_f32_ubyte0_e32 v20, v19
	v_add_u32_e32 v19, v19, v18
	v_mul_f32_e32 v20, 0x3d490fdb, v20
	v_and_b32_e32 v19, 0x7f, v19
	v_mul_f32_e32 v20, 0.15915494, v20
	v_cos_f32_e32 v20, v20
	v_fmac_f32_e32 v4, v94, v22
	v_cvt_f32_ubyte0_e32 v21, v19
	v_add_u32_e32 v19, v19, v18
	v_mul_f32_e32 v21, 0x3d490fdb, v21
	v_and_b32_e32 v19, 0x7f, v19
	v_mul_f32_e32 v21, 0.15915494, v21
	v_cos_f32_e32 v21, v21
	v_fmac_f32_e32 v4, v95, v23
	v_cvt_f32_ubyte0_e32 v22, v19
	v_add_u32_e32 v19, v19, v18
	v_mul_f32_e32 v22, 0x3d490fdb, v22
	v_and_b32_e32 v19, 0x7f, v19
	v_mul_f32_e32 v22, 0.15915494, v22
	v_cos_f32_e32 v22, v22
	v_fmac_f32_e32 v4, v96, v20
	v_cvt_f32_ubyte0_e32 v23, v19
	v_add_u32_e32 v19, v19, v18
	v_mul_f32_e32 v23, 0x3d490fdb, v23
	v_and_b32_e32 v19, 0x7f, v19
	v_mul_f32_e32 v23, 0.15915494, v23
	v_cos_f32_e32 v23, v23
	v_fmac_f32_e32 v4, v97, v21
	v_cvt_f32_ubyte0_e32 v20, v19
	v_add_u32_e32 v19, v19, v18
	v_mul_f32_e32 v20, 0x3d490fdb, v20
	v_and_b32_e32 v19, 0x7f, v19
	v_mul_f32_e32 v20, 0.15915494, v20
	v_cos_f32_e32 v20, v20
	v_fmac_f32_e32 v4, v98, v22
	v_cvt_f32_ubyte0_e32 v21, v19
	v_add_u32_e32 v19, v19, v18
	v_mul_f32_e32 v21, 0x3d490fdb, v21
	v_and_b32_e32 v19, 0x7f, v19
	v_mul_f32_e32 v21, 0.15915494, v21
	v_cos_f32_e32 v21, v21
	v_fmac_f32_e32 v4, v99, v23
	v_cvt_f32_ubyte0_e32 v22, v19
	v_add_u32_e32 v19, v19, v18
	v_mul_f32_e32 v22, 0x3d490fdb, v22
	v_and_b32_e32 v19, 0x7f, v19
	v_mul_f32_e32 v22, 0.15915494, v22
	v_cos_f32_e32 v22, v22
	v_fmac_f32_e32 v4, v100, v20
	v_cvt_f32_ubyte0_e32 v23, v19
	v_add_u32_e32 v19, v19, v18
	v_mul_f32_e32 v23, 0x3d490fdb, v23
	v_and_b32_e32 v19, 0x7f, v19
	v_mul_f32_e32 v23, 0.15915494, v23
	v_cos_f32_e32 v23, v23
	v_fmac_f32_e32 v4, v101, v21
	v_cvt_f32_ubyte0_e32 v20, v19
	v_add_u32_e32 v19, v19, v18
	v_mul_f32_e32 v20, 0x3d490fdb, v20
	v_and_b32_e32 v19, 0x7f, v19
	v_mul_f32_e32 v20, 0.15915494, v20
	v_cos_f32_e32 v20, v20
	v_fmac_f32_e32 v4, v102, v22
	v_cvt_f32_ubyte0_e32 v21, v19
	v_add_u32_e32 v19, v19, v18
	v_mul_f32_e32 v21, 0x3d490fdb, v21
	v_and_b32_e32 v19, 0x7f, v19
	v_mul_f32_e32 v21, 0.15915494, v21
	v_cos_f32_e32 v21, v21
	v_fmac_f32_e32 v4, v103, v23
	v_cvt_f32_ubyte0_e32 v22, v19
	v_add_u32_e32 v19, v19, v18
	v_mul_f32_e32 v22, 0x3d490fdb, v22
	v_and_b32_e32 v19, 0x7f, v19
	v_mul_f32_e32 v22, 0.15915494, v22
	v_cos_f32_e32 v22, v22
	v_fmac_f32_e32 v4, v104, v20
	v_cvt_f32_ubyte0_e32 v23, v19
	v_add_u32_e32 v19, v19, v18
	v_mul_f32_e32 v23, 0x3d490fdb, v23
	v_and_b32_e32 v19, 0x7f, v19
	v_mul_f32_e32 v23, 0.15915494, v23
	v_cos_f32_e32 v23, v23
	v_fmac_f32_e32 v4, v105, v21
	v_cvt_f32_ubyte0_e32 v20, v19
	v_add_u32_e32 v19, v19, v18
	v_mul_f32_e32 v20, 0x3d490fdb, v20
	v_and_b32_e32 v19, 0x7f, v19
	v_mul_f32_e32 v20, 0.15915494, v20
	v_cos_f32_e32 v20, v20
	v_fmac_f32_e32 v4, v106, v22
	v_cvt_f32_ubyte0_e32 v21, v19
	v_add_u32_e32 v19, v19, v18
	v_mul_f32_e32 v21, 0x3d490fdb, v21
	v_and_b32_e32 v19, 0x7f, v19
	v_mul_f32_e32 v21, 0.15915494, v21
	v_cos_f32_e32 v21, v21
	v_fmac_f32_e32 v4, v107, v23
	v_cvt_f32_ubyte0_e32 v22, v19
	v_add_u32_e32 v19, v19, v18
	v_mul_f32_e32 v22, 0x3d490fdb, v22
	v_and_b32_e32 v19, 0x7f, v19
	v_mul_f32_e32 v22, 0.15915494, v22
	v_cos_f32_e32 v22, v22
	v_fmac_f32_e32 v4, v108, v20
	v_cvt_f32_ubyte0_e32 v23, v19
	v_add_u32_e32 v19, v19, v18
	v_mul_f32_e32 v23, 0x3d490fdb, v23
	v_and_b32_e32 v19, 0x7f, v19
	v_mul_f32_e32 v23, 0.15915494, v23
	v_cos_f32_e32 v23, v23
	v_fmac_f32_e32 v4, v109, v21
	v_cvt_f32_ubyte0_e32 v20, v19
	v_add_u32_e32 v19, v19, v18
	v_mul_f32_e32 v20, 0x3d490fdb, v20
	v_and_b32_e32 v19, 0x7f, v19
	v_mul_f32_e32 v20, 0.15915494, v20
	v_cos_f32_e32 v20, v20
	v_fmac_f32_e32 v4, v110, v22
	v_cvt_f32_ubyte0_e32 v21, v19
	v_add_u32_e32 v19, v19, v18
	v_mul_f32_e32 v21, 0x3d490fdb, v21
	v_and_b32_e32 v19, 0x7f, v19
	v_mul_f32_e32 v21, 0.15915494, v21
	v_cos_f32_e32 v21, v21
	v_fmac_f32_e32 v4, v111, v23
	v_cvt_f32_ubyte0_e32 v22, v19
	v_add_u32_e32 v19, v19, v18
	v_mul_f32_e32 v22, 0x3d490fdb, v22
	v_and_b32_e32 v19, 0x7f, v19
	v_mul_f32_e32 v22, 0.15915494, v22
	v_cos_f32_e32 v22, v22
	v_fmac_f32_e32 v4, v112, v20
	v_cvt_f32_ubyte0_e32 v23, v19
	v_add_u32_e32 v19, v19, v18
	v_mul_f32_e32 v23, 0x3d490fdb, v23
	v_and_b32_e32 v19, 0x7f, v19
	v_mul_f32_e32 v23, 0.15915494, v23
	v_cos_f32_e32 v23, v23
	v_fmac_f32_e32 v4, v113, v21
	v_cvt_f32_ubyte0_e32 v20, v19
	v_add_u32_e32 v19, v19, v18
	v_mul_f32_e32 v20, 0x3d490fdb, v20
	v_and_b32_e32 v19, 0x7f, v19
	v_mul_f32_e32 v20, 0.15915494, v20
	v_cos_f32_e32 v20, v20
	v_fmac_f32_e32 v4, v114, v22
	v_cvt_f32_ubyte0_e32 v21, v19
	v_add_u32_e32 v19, v19, v18
	v_mul_f32_e32 v21, 0x3d490fdb, v21
	v_and_b32_e32 v19, 0x7f, v19
	v_mul_f32_e32 v21, 0.15915494, v21
	v_cos_f32_e32 v21, v21
	v_fmac_f32_e32 v4, v115, v23
	v_cvt_f32_ubyte0_e32 v22, v19
	v_add_u32_e32 v19, v19, v18
	v_mul_f32_e32 v22, 0x3d490fdb, v22
	v_and_b32_e32 v19, 0x7f, v19
	v_mul_f32_e32 v22, 0.15915494, v22
	v_cos_f32_e32 v22, v22
	v_fmac_f32_e32 v4, v116, v20
	v_cvt_f32_ubyte0_e32 v23, v19
	v_add_u32_e32 v19, v19, v18
	v_mul_f32_e32 v23, 0x3d490fdb, v23
	v_and_b32_e32 v19, 0x7f, v19
	v_mul_f32_e32 v23, 0.15915494, v23
	v_cos_f32_e32 v23, v23
	v_fmac_f32_e32 v4, v117, v21
	v_cvt_f32_ubyte0_e32 v20, v19
	v_add_u32_e32 v19, v19, v18
	v_mul_f32_e32 v20, 0x3d490fdb, v20
	v_and_b32_e32 v19, 0x7f, v19
	v_mul_f32_e32 v20, 0.15915494, v20
	v_cos_f32_e32 v20, v20
	v_fmac_f32_e32 v4, v118, v22
	v_cvt_f32_ubyte0_e32 v21, v19
	v_add_u32_e32 v19, v19, v18
	v_mul_f32_e32 v21, 0x3d490fdb, v21
	v_and_b32_e32 v19, 0x7f, v19
	v_mul_f32_e32 v21, 0.15915494, v21
	v_cos_f32_e32 v21, v21
	v_fmac_f32_e32 v4, v119, v23
	v_cvt_f32_ubyte0_e32 v22, v19
	v_add_u32_e32 v19, v19, v18
	v_mul_f32_e32 v22, 0x3d490fdb, v22
	v_and_b32_e32 v19, 0x7f, v19
	v_mul_f32_e32 v22, 0.15915494, v22
	v_cos_f32_e32 v22, v22
	v_fmac_f32_e32 v4, v120, v20
	v_cvt_f32_ubyte0_e32 v23, v19
	v_add_u32_e32 v19, v19, v18
	v_mul_f32_e32 v23, 0x3d490fdb, v23
	v_and_b32_e32 v19, 0x7f, v19
	v_mul_f32_e32 v23, 0.15915494, v23
	v_cos_f32_e32 v23, v23
	v_fmac_f32_e32 v4, v121, v21
	v_cvt_f32_ubyte0_e32 v20, v19
	v_add_u32_e32 v19, v19, v18
	v_mul_f32_e32 v20, 0x3d490fdb, v20
	v_and_b32_e32 v19, 0x7f, v19
	v_mul_f32_e32 v20, 0.15915494, v20
	v_cos_f32_e32 v20, v20
	v_fmac_f32_e32 v4, v122, v22
	v_cvt_f32_ubyte0_e32 v21, v19
	v_add_u32_e32 v19, v19, v18
	v_mul_f32_e32 v21, 0x3d490fdb, v21
	v_and_b32_e32 v19, 0x7f, v19
	v_mul_f32_e32 v21, 0.15915494, v21
	v_cos_f32_e32 v21, v21
	v_fmac_f32_e32 v4, v123, v23
	v_cvt_f32_ubyte0_e32 v22, v19
	v_add_u32_e32 v19, v19, v18
	v_mul_f32_e32 v22, 0x3d490fdb, v22
	v_and_b32_e32 v19, 0x7f, v19
	v_mul_f32_e32 v22, 0.15915494, v22
	v_cos_f32_e32 v22, v22
	v_fmac_f32_e32 v4, v124, v20
	v_cvt_f32_ubyte0_e32 v23, v19
	v_add_u32_e32 v19, v19, v18
	v_mul_f32_e32 v23, 0x3d490fdb, v23
	v_and_b32_e32 v19, 0x7f, v19
	v_mul_f32_e32 v23, 0.15915494, v23
	v_cos_f32_e32 v23, v23
	v_fmac_f32_e32 v4, v125, v21
	v_cvt_f32_ubyte0_e32 v20, v19
	v_add_u32_e32 v19, v19, v18
	v_mul_f32_e32 v20, 0x3d490fdb, v20
	v_and_b32_e32 v19, 0x7f, v19
	v_mul_f32_e32 v20, 0.15915494, v20
	v_cos_f32_e32 v20, v20
	v_fmac_f32_e32 v4, v126, v22
	v_cvt_f32_ubyte0_e32 v21, v19
	v_add_u32_e32 v19, v19, v18
	v_mul_f32_e32 v21, 0x3d490fdb, v21
	v_and_b32_e32 v19, 0x7f, v19
	v_mul_f32_e32 v21, 0.15915494, v21
	v_cos_f32_e32 v21, v21
	v_fmac_f32_e32 v4, v127, v23
	v_cvt_f32_ubyte0_e32 v22, v19
	v_add_u32_e32 v19, v19, v18
	v_mul_f32_e32 v22, 0x3d490fdb, v22
	v_and_b32_e32 v19, 0x7f, v19
	v_mul_f32_e32 v22, 0.15915494, v22
	v_cos_f32_e32 v22, v22
	v_fmac_f32_e32 v4, v128, v20
	v_cvt_f32_ubyte0_e32 v23, v19
	v_add_u32_e32 v19, v19, v18
	v_mul_f32_e32 v23, 0x3d490fdb, v23
	v_and_b32_e32 v19, 0x7f, v19
	v_mul_f32_e32 v23, 0.15915494, v23
	v_cos_f32_e32 v23, v23
	v_fmac_f32_e32 v4, v129, v21
	v_cvt_f32_ubyte0_e32 v20, v19
	v_add_u32_e32 v19, v19, v18
	v_mul_f32_e32 v20, 0x3d490fdb, v20
	v_and_b32_e32 v19, 0x7f, v19
	v_mul_f32_e32 v20, 0.15915494, v20
	v_cos_f32_e32 v20, v20
	v_fmac_f32_e32 v4, v130, v22
	v_cvt_f32_ubyte0_e32 v21, v19
	v_add_u32_e32 v19, v19, v18
	v_mul_f32_e32 v21, 0x3d490fdb, v21
	v_and_b32_e32 v19, 0x7f, v19
	v_mul_f32_e32 v21, 0.15915494, v21
	v_cos_f32_e32 v21, v21
	v_fmac_f32_e32 v4, v131, v23
	v_cvt_f32_ubyte0_e32 v22, v19
	v_add_u32_e32 v19, v19, v18
	v_mul_f32_e32 v22, 0x3d490fdb, v22
	v_and_b32_e32 v19, 0x7f, v19
	v_mul_f32_e32 v22, 0.15915494, v22
	v_cos_f32_e32 v22, v22
	v_fmac_f32_e32 v4, v132, v20
	v_cvt_f32_ubyte0_e32 v23, v19
	v_add_u32_e32 v19, v19, v18
	v_mul_f32_e32 v23, 0x3d490fdb, v23
	v_and_b32_e32 v19, 0x7f, v19
	v_mul_f32_e32 v23, 0.15915494, v23
	v_cos_f32_e32 v23, v23
	v_fmac_f32_e32 v4, v133, v21
	v_cvt_f32_ubyte0_e32 v20, v19
	v_add_u32_e32 v19, v19, v18
	v_mul_f32_e32 v20, 0x3d490fdb, v20
	v_and_b32_e32 v19, 0x7f, v19
	v_mul_f32_e32 v20, 0.15915494, v20
	v_cos_f32_e32 v20, v20
	v_fmac_f32_e32 v4, v134, v22
	v_cvt_f32_ubyte0_e32 v21, v19
	v_add_u32_e32 v19, v19, v18
	v_mul_f32_e32 v21, 0x3d490fdb, v21
	v_and_b32_e32 v19, 0x7f, v19
	v_mul_f32_e32 v21, 0.15915494, v21
	v_cos_f32_e32 v21, v21
	v_fmac_f32_e32 v4, v135, v23
	v_cvt_f32_ubyte0_e32 v22, v19
	v_add_u32_e32 v19, v19, v18
	v_mul_f32_e32 v22, 0x3d490fdb, v22
	v_and_b32_e32 v19, 0x7f, v19
	v_mul_f32_e32 v22, 0.15915494, v22
	v_cos_f32_e32 v22, v22
	v_fmac_f32_e32 v4, v136, v20
	v_cvt_f32_ubyte0_e32 v23, v19
	v_add_u32_e32 v19, v19, v18
	v_mul_f32_e32 v23, 0x3d490fdb, v23
	v_and_b32_e32 v19, 0x7f, v19
	v_mul_f32_e32 v23, 0.15915494, v23
	v_cos_f32_e32 v23, v23
	v_fmac_f32_e32 v4, v137, v21
	v_cvt_f32_ubyte0_e32 v20, v19
	v_add_u32_e32 v19, v19, v18
	v_mul_f32_e32 v20, 0x3d490fdb, v20
	v_and_b32_e32 v19, 0x7f, v19
	v_mul_f32_e32 v20, 0.15915494, v20
	v_cos_f32_e32 v20, v20
	v_fmac_f32_e32 v4, v138, v22
	v_cvt_f32_ubyte0_e32 v21, v19
	v_add_u32_e32 v19, v19, v18
	v_mul_f32_e32 v21, 0x3d490fdb, v21
	v_and_b32_e32 v19, 0x7f, v19
	v_mul_f32_e32 v21, 0.15915494, v21
	v_cos_f32_e32 v21, v21
	v_fmac_f32_e32 v4, v139, v23
	v_cvt_f32_ubyte0_e32 v22, v19
	v_add_u32_e32 v19, v19, v18
	v_mul_f32_e32 v22, 0x3d490fdb, v22
	v_and_b32_e32 v19, 0x7f, v19
	v_mul_f32_e32 v22, 0.15915494, v22
	v_cos_f32_e32 v22, v22
	v_fmac_f32_e32 v4, v140, v20
	v_cvt_f32_ubyte0_e32 v23, v19
	v_add_u32_e32 v19, v19, v18
	v_mul_f32_e32 v23, 0x3d490fdb, v23
	v_and_b32_e32 v19, 0x7f, v19
	v_mul_f32_e32 v23, 0.15915494, v23
	v_cos_f32_e32 v23, v23
	v_fmac_f32_e32 v4, v141, v21
	v_cvt_f32_ubyte0_e32 v20, v19
	v_add_u32_e32 v19, v19, v18
	v_mul_f32_e32 v20, 0x3d490fdb, v20
	v_and_b32_e32 v19, 0x7f, v19
	v_mul_f32_e32 v20, 0.15915494, v20
	v_cos_f32_e32 v20, v20
	v_fmac_f32_e32 v4, v142, v22
	v_cvt_f32_ubyte0_e32 v21, v19
	v_add_u32_e32 v19, v19, v18
	v_mul_f32_e32 v21, 0x3d490fdb, v21
	v_and_b32_e32 v19, 0x7f, v19
	v_mul_f32_e32 v21, 0.15915494, v21
	v_cos_f32_e32 v21, v21
	v_fmac_f32_e32 v4, v143, v23
	v_cvt_f32_ubyte0_e32 v22, v19
	v_add_u32_e32 v19, v19, v18
	v_mul_f32_e32 v22, 0x3d490fdb, v22
	v_and_b32_e32 v19, 0x7f, v19
	v_mul_f32_e32 v22, 0.15915494, v22
	v_cos_f32_e32 v22, v22
	v_fmac_f32_e32 v4, v144, v20
	v_cvt_f32_ubyte0_e32 v23, v19
	v_add_u32_e32 v19, v19, v18
	v_mul_f32_e32 v23, 0x3d490fdb, v23
	v_and_b32_e32 v19, 0x7f, v19
	v_mul_f32_e32 v23, 0.15915494, v23
	v_cos_f32_e32 v23, v23
	v_fmac_f32_e32 v4, v145, v21
	v_cvt_f32_ubyte0_e32 v20, v19
	v_add_u32_e32 v19, v19, v18
	v_mul_f32_e32 v20, 0x3d490fdb, v20
	v_and_b32_e32 v19, 0x7f, v19
	v_mul_f32_e32 v20, 0.15915494, v20
	v_cos_f32_e32 v20, v20
	v_fmac_f32_e32 v4, v146, v22
	v_cvt_f32_ubyte0_e32 v21, v19
	v_add_u32_e32 v19, v19, v18
	v_mul_f32_e32 v21, 0x3d490fdb, v21
	v_and_b32_e32 v19, 0x7f, v19
	v_mul_f32_e32 v21, 0.15915494, v21
	v_cos_f32_e32 v21, v21
	v_fmac_f32_e32 v4, v147, v23
	v_cvt_f32_ubyte0_e32 v22, v19
	v_add_u32_e32 v19, v19, v18
	v_mul_f32_e32 v22, 0x3d490fdb, v22
	v_and_b32_e32 v19, 0x7f, v19
	v_mul_f32_e32 v22, 0.15915494, v22
	v_cos_f32_e32 v22, v22
	s_waitcnt vmcnt(63)
	v_fmac_f32_e32 v4, v148, v20
	v_cvt_f32_ubyte0_e32 v23, v19
	v_add_u32_e32 v19, v19, v18
	v_mul_f32_e32 v23, 0x3d490fdb, v23
	v_and_b32_e32 v19, 0x7f, v19
	v_mul_f32_e32 v23, 0.15915494, v23
	v_cos_f32_e32 v23, v23
	s_waitcnt vmcnt(62)
	v_fmac_f32_e32 v4, v149, v21
	v_cvt_f32_ubyte0_e32 v20, v19
	v_add_u32_e32 v19, v19, v18
	v_mul_f32_e32 v20, 0x3d490fdb, v20
	v_and_b32_e32 v19, 0x7f, v19
	v_mul_f32_e32 v20, 0.15915494, v20
	v_cos_f32_e32 v20, v20
	s_waitcnt vmcnt(61)
	v_fmac_f32_e32 v4, v150, v22
	v_cvt_f32_ubyte0_e32 v21, v19
	v_add_u32_e32 v19, v19, v18
	v_mul_f32_e32 v21, 0x3d490fdb, v21
	v_and_b32_e32 v19, 0x7f, v19
	v_mul_f32_e32 v21, 0.15915494, v21
	v_cos_f32_e32 v21, v21
	s_waitcnt vmcnt(60)
	v_fmac_f32_e32 v4, v151, v23
	v_cvt_f32_ubyte0_e32 v22, v19
	v_add_u32_e32 v19, v19, v18
	v_mul_f32_e32 v22, 0x3d490fdb, v22
	v_and_b32_e32 v19, 0x7f, v19
	v_mul_f32_e32 v22, 0.15915494, v22
	v_cos_f32_e32 v22, v22
	s_waitcnt vmcnt(59)
	v_fmac_f32_e32 v4, v152, v20
	v_cvt_f32_ubyte0_e32 v23, v19
	v_add_u32_e32 v19, v19, v18
	v_mul_f32_e32 v23, 0x3d490fdb, v23
	v_and_b32_e32 v19, 0x7f, v19
	v_mul_f32_e32 v23, 0.15915494, v23
	v_cos_f32_e32 v23, v23
	s_waitcnt vmcnt(58)
	v_fmac_f32_e32 v4, v153, v21
	v_cvt_f32_ubyte0_e32 v20, v19
	v_add_u32_e32 v19, v19, v18
	v_mul_f32_e32 v20, 0x3d490fdb, v20
	v_and_b32_e32 v19, 0x7f, v19
	v_mul_f32_e32 v20, 0.15915494, v20
	v_cos_f32_e32 v20, v20
	s_waitcnt vmcnt(57)
	v_fmac_f32_e32 v4, v154, v22
	v_cvt_f32_ubyte0_e32 v21, v19
	v_add_u32_e32 v19, v19, v18
	v_mul_f32_e32 v21, 0x3d490fdb, v21
	v_and_b32_e32 v19, 0x7f, v19
	v_mul_f32_e32 v21, 0.15915494, v21
	v_cos_f32_e32 v21, v21
	s_waitcnt vmcnt(56)
	v_fmac_f32_e32 v4, v155, v23
	v_cvt_f32_ubyte0_e32 v22, v19
	v_add_u32_e32 v19, v19, v18
	v_mul_f32_e32 v22, 0x3d490fdb, v22
	v_and_b32_e32 v19, 0x7f, v19
	v_mul_f32_e32 v22, 0.15915494, v22
	v_cos_f32_e32 v22, v22
	s_waitcnt vmcnt(55)
	v_fmac_f32_e32 v4, v156, v20
	v_cvt_f32_ubyte0_e32 v23, v19
	v_add_u32_e32 v19, v19, v18
	v_mul_f32_e32 v23, 0x3d490fdb, v23
	v_and_b32_e32 v19, 0x7f, v19
	v_mul_f32_e32 v23, 0.15915494, v23
	v_cos_f32_e32 v23, v23
	s_waitcnt vmcnt(54)
	v_fmac_f32_e32 v4, v157, v21
	v_cvt_f32_ubyte0_e32 v20, v19
	v_add_u32_e32 v19, v19, v18
	v_mul_f32_e32 v20, 0x3d490fdb, v20
	v_and_b32_e32 v19, 0x7f, v19
	v_mul_f32_e32 v20, 0.15915494, v20
	v_cos_f32_e32 v20, v20
	s_waitcnt vmcnt(53)
	v_fmac_f32_e32 v4, v158, v22
	v_cvt_f32_ubyte0_e32 v21, v19
	v_add_u32_e32 v19, v19, v18
	v_mul_f32_e32 v21, 0x3d490fdb, v21
	v_and_b32_e32 v19, 0x7f, v19
	v_mul_f32_e32 v21, 0.15915494, v21
	v_cos_f32_e32 v21, v21
	s_waitcnt vmcnt(52)
	v_fmac_f32_e32 v4, v159, v23
	v_cvt_f32_ubyte0_e32 v22, v19
	v_add_u32_e32 v19, v19, v18
	v_mul_f32_e32 v22, 0x3d490fdb, v22
	v_and_b32_e32 v19, 0x7f, v19
	v_mul_f32_e32 v22, 0.15915494, v22
	v_cos_f32_e32 v22, v22
	s_waitcnt vmcnt(51)
	v_fmac_f32_e32 v4, v160, v20
	v_cvt_f32_ubyte0_e32 v23, v19
	v_add_u32_e32 v19, v19, v18
	v_mul_f32_e32 v23, 0x3d490fdb, v23
	v_and_b32_e32 v19, 0x7f, v19
	v_mul_f32_e32 v23, 0.15915494, v23
	v_cos_f32_e32 v23, v23
	s_waitcnt vmcnt(50)
	v_fmac_f32_e32 v4, v161, v21
	v_cvt_f32_ubyte0_e32 v20, v19
	v_add_u32_e32 v19, v19, v18
	v_mul_f32_e32 v20, 0x3d490fdb, v20
	v_and_b32_e32 v19, 0x7f, v19
	v_mul_f32_e32 v20, 0.15915494, v20
	v_cos_f32_e32 v20, v20
	s_waitcnt vmcnt(49)
	v_fmac_f32_e32 v4, v162, v22
	v_cvt_f32_ubyte0_e32 v21, v19
	v_add_u32_e32 v19, v19, v18
	v_mul_f32_e32 v21, 0x3d490fdb, v21
	v_and_b32_e32 v19, 0x7f, v19
	v_mul_f32_e32 v21, 0.15915494, v21
	v_cos_f32_e32 v21, v21
	s_waitcnt vmcnt(48)
	v_fmac_f32_e32 v4, v163, v23
	v_cvt_f32_ubyte0_e32 v22, v19
	v_add_u32_e32 v19, v19, v18
	v_mul_f32_e32 v22, 0x3d490fdb, v22
	v_and_b32_e32 v19, 0x7f, v19
	v_mul_f32_e32 v22, 0.15915494, v22
	v_cos_f32_e32 v22, v22
	s_waitcnt vmcnt(47)
	v_fmac_f32_e32 v4, v164, v20
	v_cvt_f32_ubyte0_e32 v23, v19
	v_add_u32_e32 v19, v19, v18
	v_mul_f32_e32 v23, 0x3d490fdb, v23
	v_and_b32_e32 v19, 0x7f, v19
	v_mul_f32_e32 v23, 0.15915494, v23
	v_cos_f32_e32 v23, v23
	s_waitcnt vmcnt(46)
	v_fmac_f32_e32 v4, v165, v21
	v_cvt_f32_ubyte0_e32 v20, v19
	v_add_u32_e32 v19, v19, v18
	v_mul_f32_e32 v20, 0x3d490fdb, v20
	v_and_b32_e32 v19, 0x7f, v19
	v_mul_f32_e32 v20, 0.15915494, v20
	v_cos_f32_e32 v20, v20
	s_waitcnt vmcnt(45)
	v_fmac_f32_e32 v4, v166, v22
	v_cvt_f32_ubyte0_e32 v21, v19
	v_add_u32_e32 v19, v19, v18
	v_mul_f32_e32 v21, 0x3d490fdb, v21
	v_and_b32_e32 v19, 0x7f, v19
	v_mul_f32_e32 v21, 0.15915494, v21
	v_cos_f32_e32 v21, v21
	s_waitcnt vmcnt(44)
	v_fmac_f32_e32 v4, v167, v23
	v_cvt_f32_ubyte0_e32 v22, v19
	v_add_u32_e32 v19, v19, v18
	v_mul_f32_e32 v22, 0x3d490fdb, v22
	v_and_b32_e32 v19, 0x7f, v19
	v_mul_f32_e32 v22, 0.15915494, v22
	v_cos_f32_e32 v22, v22
	s_waitcnt vmcnt(43)
	v_fmac_f32_e32 v4, v168, v20
	v_cvt_f32_ubyte0_e32 v23, v19
	v_add_u32_e32 v19, v19, v18
	v_mul_f32_e32 v23, 0x3d490fdb, v23
	v_and_b32_e32 v19, 0x7f, v19
	v_mul_f32_e32 v23, 0.15915494, v23
	v_cos_f32_e32 v23, v23
	s_waitcnt vmcnt(42)
	v_fmac_f32_e32 v4, v169, v21
	v_cvt_f32_ubyte0_e32 v20, v19
	v_add_u32_e32 v19, v19, v18
	v_mul_f32_e32 v20, 0x3d490fdb, v20
	v_and_b32_e32 v19, 0x7f, v19
	v_mul_f32_e32 v20, 0.15915494, v20
	v_cos_f32_e32 v20, v20
	s_waitcnt vmcnt(41)
	v_fmac_f32_e32 v4, v170, v22
	v_cvt_f32_ubyte0_e32 v21, v19
	v_add_u32_e32 v19, v19, v18
	v_mul_f32_e32 v21, 0x3d490fdb, v21
	v_and_b32_e32 v19, 0x7f, v19
	v_mul_f32_e32 v21, 0.15915494, v21
	v_cos_f32_e32 v21, v21
	s_waitcnt vmcnt(40)
	v_fmac_f32_e32 v4, v171, v23
	v_cvt_f32_ubyte0_e32 v22, v19
	v_add_u32_e32 v19, v19, v18
	v_mul_f32_e32 v22, 0x3d490fdb, v22
	v_and_b32_e32 v19, 0x7f, v19
	v_mul_f32_e32 v22, 0.15915494, v22
	v_cos_f32_e32 v22, v22
	s_waitcnt vmcnt(39)
	v_fmac_f32_e32 v4, v172, v20
	v_cvt_f32_ubyte0_e32 v23, v19
	v_add_u32_e32 v19, v19, v18
	v_mul_f32_e32 v23, 0x3d490fdb, v23
	v_and_b32_e32 v19, 0x7f, v19
	v_mul_f32_e32 v23, 0.15915494, v23
	v_cos_f32_e32 v23, v23
	s_waitcnt vmcnt(38)
	v_fmac_f32_e32 v4, v173, v21
	v_cvt_f32_ubyte0_e32 v20, v19
	v_add_u32_e32 v19, v19, v18
	v_mul_f32_e32 v20, 0x3d490fdb, v20
	v_and_b32_e32 v19, 0x7f, v19
	v_mul_f32_e32 v20, 0.15915494, v20
	v_cos_f32_e32 v20, v20
	s_waitcnt vmcnt(37)
	v_fmac_f32_e32 v4, v174, v22
	v_cvt_f32_ubyte0_e32 v21, v19
	v_add_u32_e32 v19, v19, v18
	v_mul_f32_e32 v21, 0x3d490fdb, v21
	v_and_b32_e32 v19, 0x7f, v19
	v_mul_f32_e32 v21, 0.15915494, v21
	v_cos_f32_e32 v21, v21
	s_waitcnt vmcnt(36)
	v_fmac_f32_e32 v4, v175, v23
	v_cvt_f32_ubyte0_e32 v22, v19
	v_add_u32_e32 v19, v19, v18
	v_mul_f32_e32 v22, 0x3d490fdb, v22
	v_and_b32_e32 v19, 0x7f, v19
	v_mul_f32_e32 v22, 0.15915494, v22
	v_cos_f32_e32 v22, v22
	s_waitcnt vmcnt(35)
	v_fmac_f32_e32 v4, v178, v20
	v_cvt_f32_ubyte0_e32 v23, v19
	v_add_u32_e32 v19, v19, v18
	v_mul_f32_e32 v23, 0x3d490fdb, v23
	v_and_b32_e32 v19, 0x7f, v19
	v_mul_f32_e32 v23, 0.15915494, v23
	v_cos_f32_e32 v23, v23
	s_waitcnt vmcnt(34)
	v_fmac_f32_e32 v4, v179, v21
	v_cvt_f32_ubyte0_e32 v20, v19
	v_add_u32_e32 v19, v19, v18
	v_mul_f32_e32 v20, 0x3d490fdb, v20
	v_and_b32_e32 v19, 0x7f, v19
	v_mul_f32_e32 v20, 0.15915494, v20
	v_cos_f32_e32 v20, v20
	s_waitcnt vmcnt(33)
	v_fmac_f32_e32 v4, v180, v22
	v_cvt_f32_ubyte0_e32 v21, v19
	v_add_u32_e32 v19, v19, v18
	v_mul_f32_e32 v21, 0x3d490fdb, v21
	v_and_b32_e32 v19, 0x7f, v19
	v_mul_f32_e32 v21, 0.15915494, v21
	v_cos_f32_e32 v21, v21
	s_waitcnt vmcnt(32)
	v_fmac_f32_e32 v4, v181, v23
	v_cvt_f32_ubyte0_e32 v22, v19
	v_add_u32_e32 v19, v19, v18
	v_mul_f32_e32 v22, 0x3d490fdb, v22
	v_and_b32_e32 v19, 0x7f, v19
	v_mul_f32_e32 v22, 0.15915494, v22
	v_cos_f32_e32 v22, v22
	s_waitcnt vmcnt(31)
	v_fmac_f32_e32 v4, v182, v20
	v_cvt_f32_ubyte0_e32 v23, v19
	v_add_u32_e32 v19, v19, v18
	v_mul_f32_e32 v23, 0x3d490fdb, v23
	v_and_b32_e32 v19, 0x7f, v19
	v_mul_f32_e32 v23, 0.15915494, v23
	v_cos_f32_e32 v23, v23
	s_waitcnt vmcnt(30)
	v_fmac_f32_e32 v4, v183, v21
	v_cvt_f32_ubyte0_e32 v20, v19
	v_add_u32_e32 v19, v19, v18
	v_mul_f32_e32 v20, 0x3d490fdb, v20
	v_and_b32_e32 v19, 0x7f, v19
	v_mul_f32_e32 v20, 0.15915494, v20
	v_cos_f32_e32 v20, v20
	s_waitcnt vmcnt(29)
	v_fmac_f32_e32 v4, v184, v22
	v_cvt_f32_ubyte0_e32 v21, v19
	v_add_u32_e32 v19, v19, v18
	v_mul_f32_e32 v21, 0x3d490fdb, v21
	v_and_b32_e32 v19, 0x7f, v19
	v_mul_f32_e32 v21, 0.15915494, v21
	v_cos_f32_e32 v21, v21
	s_waitcnt vmcnt(28)
	v_fmac_f32_e32 v4, v185, v23
	v_cvt_f32_ubyte0_e32 v22, v19
	v_add_u32_e32 v19, v19, v18
	v_mul_f32_e32 v22, 0x3d490fdb, v22
	v_and_b32_e32 v19, 0x7f, v19
	v_mul_f32_e32 v22, 0.15915494, v22
	v_cos_f32_e32 v22, v22
	s_waitcnt vmcnt(27)
	v_fmac_f32_e32 v4, v186, v20
	v_cvt_f32_ubyte0_e32 v23, v19
	v_add_u32_e32 v19, v19, v18
	v_mul_f32_e32 v23, 0x3d490fdb, v23
	v_and_b32_e32 v19, 0x7f, v19
	v_mul_f32_e32 v23, 0.15915494, v23
	v_cos_f32_e32 v23, v23
	s_waitcnt vmcnt(26)
	v_fmac_f32_e32 v4, v187, v21
	v_cvt_f32_ubyte0_e32 v20, v19
	v_add_u32_e32 v19, v19, v18
	v_mul_f32_e32 v20, 0x3d490fdb, v20
	v_and_b32_e32 v19, 0x7f, v19
	v_mul_f32_e32 v20, 0.15915494, v20
	v_cos_f32_e32 v20, v20
	s_waitcnt vmcnt(25)
	v_fmac_f32_e32 v4, v188, v22
	v_cvt_f32_ubyte0_e32 v21, v19
	v_add_u32_e32 v19, v19, v18
	v_mul_f32_e32 v21, 0x3d490fdb, v21
	v_and_b32_e32 v19, 0x7f, v19
	v_mul_f32_e32 v21, 0.15915494, v21
	v_cos_f32_e32 v21, v21
	s_waitcnt vmcnt(24)
	v_fmac_f32_e32 v4, v189, v23
	v_cvt_f32_ubyte0_e32 v22, v19
	v_add_u32_e32 v19, v19, v18
	v_mul_f32_e32 v22, 0x3d490fdb, v22
	v_and_b32_e32 v19, 0x7f, v19
	v_mul_f32_e32 v22, 0.15915494, v22
	v_cos_f32_e32 v22, v22
	s_waitcnt vmcnt(23)
	v_fmac_f32_e32 v4, v190, v20
	v_cvt_f32_ubyte0_e32 v23, v19
	v_add_u32_e32 v19, v19, v18
	v_mul_f32_e32 v23, 0x3d490fdb, v23
	v_and_b32_e32 v19, 0x7f, v19
	v_mul_f32_e32 v23, 0.15915494, v23
	v_cos_f32_e32 v23, v23
	s_waitcnt vmcnt(22)
	v_fmac_f32_e32 v4, v191, v21
	v_cvt_f32_ubyte0_e32 v20, v19
	v_add_u32_e32 v19, v19, v18
	v_mul_f32_e32 v20, 0x3d490fdb, v20
	v_and_b32_e32 v19, 0x7f, v19
	v_mul_f32_e32 v20, 0.15915494, v20
	v_cos_f32_e32 v20, v20
	s_waitcnt vmcnt(21)
	v_fmac_f32_e32 v4, v192, v22
	v_cvt_f32_ubyte0_e32 v21, v19
	v_add_u32_e32 v19, v19, v18
	v_mul_f32_e32 v21, 0x3d490fdb, v21
	v_and_b32_e32 v19, 0x7f, v19
	v_mul_f32_e32 v21, 0.15915494, v21
	v_cos_f32_e32 v21, v21
	s_waitcnt vmcnt(20)
	v_fmac_f32_e32 v4, v193, v23
	v_cvt_f32_ubyte0_e32 v22, v19
	v_add_u32_e32 v19, v19, v18
	v_mul_f32_e32 v22, 0x3d490fdb, v22
	v_and_b32_e32 v19, 0x7f, v19
	v_mul_f32_e32 v22, 0.15915494, v22
	v_cos_f32_e32 v22, v22
	s_waitcnt vmcnt(19)
	v_fmac_f32_e32 v4, v194, v20
	v_cvt_f32_ubyte0_e32 v23, v19
	v_add_u32_e32 v19, v19, v18
	v_mul_f32_e32 v23, 0x3d490fdb, v23
	v_and_b32_e32 v19, 0x7f, v19
	v_mul_f32_e32 v23, 0.15915494, v23
	v_cos_f32_e32 v23, v23
	s_waitcnt vmcnt(18)
	v_fmac_f32_e32 v4, v195, v21
	v_cvt_f32_ubyte0_e32 v20, v19
	v_add_u32_e32 v19, v19, v18
	v_mul_f32_e32 v20, 0x3d490fdb, v20
	v_and_b32_e32 v19, 0x7f, v19
	v_mul_f32_e32 v20, 0.15915494, v20
	v_cos_f32_e32 v20, v20
	s_waitcnt vmcnt(17)
	v_fmac_f32_e32 v4, v196, v22
	v_cvt_f32_ubyte0_e32 v21, v19
	v_add_u32_e32 v19, v19, v18
	v_mul_f32_e32 v21, 0x3d490fdb, v21
	v_and_b32_e32 v19, 0x7f, v19
	v_mul_f32_e32 v21, 0.15915494, v21
	v_cos_f32_e32 v21, v21
	s_waitcnt vmcnt(16)
	v_fmac_f32_e32 v4, v197, v23
	v_cvt_f32_ubyte0_e32 v22, v19
	v_add_u32_e32 v19, v19, v18
	v_mul_f32_e32 v22, 0x3d490fdb, v22
	v_and_b32_e32 v19, 0x7f, v19
	v_mul_f32_e32 v22, 0.15915494, v22
	v_cos_f32_e32 v22, v22
	s_waitcnt vmcnt(15)
	v_fmac_f32_e32 v4, v198, v20
	v_cvt_f32_ubyte0_e32 v23, v19
	v_add_u32_e32 v19, v19, v18
	v_mul_f32_e32 v23, 0x3d490fdb, v23
	v_and_b32_e32 v19, 0x7f, v19
	v_mul_f32_e32 v23, 0.15915494, v23
	v_cos_f32_e32 v23, v23
	s_waitcnt vmcnt(14)
	v_fmac_f32_e32 v4, v199, v21
	v_cvt_f32_ubyte0_e32 v20, v19
	v_add_u32_e32 v19, v19, v18
	v_mul_f32_e32 v20, 0x3d490fdb, v20
	v_and_b32_e32 v19, 0x7f, v19
	v_mul_f32_e32 v20, 0.15915494, v20
	v_cos_f32_e32 v20, v20
	s_waitcnt vmcnt(13)
	v_fmac_f32_e32 v4, v200, v22
	v_cvt_f32_ubyte0_e32 v21, v19
	v_add_u32_e32 v19, v19, v18
	v_mul_f32_e32 v21, 0x3d490fdb, v21
	v_and_b32_e32 v19, 0x7f, v19
	v_mul_f32_e32 v21, 0.15915494, v21
	v_cos_f32_e32 v21, v21
	s_waitcnt vmcnt(12)
	v_fmac_f32_e32 v4, v201, v23
	v_cvt_f32_ubyte0_e32 v22, v19
	v_add_u32_e32 v19, v19, v18
	v_mul_f32_e32 v22, 0x3d490fdb, v22
	v_and_b32_e32 v19, 0x7f, v19
	v_mul_f32_e32 v22, 0.15915494, v22
	v_cos_f32_e32 v22, v22
	s_waitcnt vmcnt(11)
	v_fmac_f32_e32 v4, v202, v20
	v_cvt_f32_ubyte0_e32 v23, v19
	v_add_u32_e32 v19, v19, v18
	v_mul_f32_e32 v23, 0x3d490fdb, v23
	v_and_b32_e32 v19, 0x7f, v19
	v_mul_f32_e32 v23, 0.15915494, v23
	v_cos_f32_e32 v23, v23
	s_waitcnt vmcnt(10)
	v_fmac_f32_e32 v4, v203, v21
	v_cvt_f32_ubyte0_e32 v20, v19
	v_add_u32_e32 v19, v19, v18
	v_mul_f32_e32 v20, 0x3d490fdb, v20
	v_and_b32_e32 v19, 0x7f, v19
	v_mul_f32_e32 v20, 0.15915494, v20
	v_cos_f32_e32 v20, v20
	s_waitcnt vmcnt(9)
	v_fmac_f32_e32 v4, v204, v22
	v_cvt_f32_ubyte0_e32 v21, v19
	v_add_u32_e32 v19, v19, v18
	v_mul_f32_e32 v21, 0x3d490fdb, v21
	v_and_b32_e32 v19, 0x7f, v19
	v_mul_f32_e32 v21, 0.15915494, v21
	v_cos_f32_e32 v21, v21
	s_waitcnt vmcnt(8)
	v_fmac_f32_e32 v4, v205, v23
	v_cvt_f32_ubyte0_e32 v22, v19
	v_add_u32_e32 v19, v19, v18
	v_mul_f32_e32 v22, 0x3d490fdb, v22
	v_and_b32_e32 v19, 0x7f, v19
	v_mul_f32_e32 v22, 0.15915494, v22
	v_cos_f32_e32 v22, v22
	s_waitcnt vmcnt(7)
	v_fmac_f32_e32 v4, v206, v20
	v_cvt_f32_ubyte0_e32 v23, v19
	v_add_u32_e32 v19, v19, v18
	v_mul_f32_e32 v23, 0x3d490fdb, v23
	v_and_b32_e32 v19, 0x7f, v19
	v_mul_f32_e32 v23, 0.15915494, v23
	v_cos_f32_e32 v23, v23
	s_waitcnt vmcnt(6)
	v_fmac_f32_e32 v4, v207, v21
	v_cvt_f32_ubyte0_e32 v20, v19
	v_add_u32_e32 v19, v19, v18
	v_mul_f32_e32 v20, 0x3d490fdb, v20
	v_and_b32_e32 v19, 0x7f, v19
	v_mul_f32_e32 v20, 0.15915494, v20
	v_cos_f32_e32 v20, v20
	s_waitcnt vmcnt(5)
	v_fmac_f32_e32 v4, v208, v22
	v_cvt_f32_ubyte0_e32 v21, v19
	v_add_u32_e32 v19, v19, v18
	v_mul_f32_e32 v21, 0x3d490fdb, v21
	v_and_b32_e32 v19, 0x7f, v19
	v_mul_f32_e32 v21, 0.15915494, v21
	v_cos_f32_e32 v21, v21
	s_waitcnt vmcnt(4)
	v_fmac_f32_e32 v4, v209, v23
	v_cvt_f32_ubyte0_e32 v22, v19
	v_add_u32_e32 v19, v19, v18
	v_mul_f32_e32 v22, 0x3d490fdb, v22
	v_and_b32_e32 v19, 0x7f, v19
	v_mul_f32_e32 v22, 0.15915494, v22
	v_cos_f32_e32 v22, v22
	s_waitcnt vmcnt(3)
	v_fmac_f32_e32 v4, v210, v20
	v_cvt_f32_ubyte0_e32 v23, v19
	v_add_u32_e32 v19, v19, v18
	v_mul_f32_e32 v23, 0x3d490fdb, v23
	v_and_b32_e32 v19, 0x7f, v19
	v_mul_f32_e32 v23, 0.15915494, v23
	v_cos_f32_e32 v23, v23
	s_waitcnt vmcnt(2)
	v_fmac_f32_e32 v4, v211, v21
	s_waitcnt vmcnt(1)
	v_fmac_f32_e32 v4, v212, v22
	s_waitcnt vmcnt(0)
	v_fmac_f32_e32 v4, v213, v23
	s_branch .Lmc_done
.Lmc_sin:
	v_cvt_f32_ubyte0_e32 v20, v19
	v_add_u32_e32 v19, v19, v18
	v_mul_f32_e32 v20, 0x3d490fdb, v20
	v_and_b32_e32 v19, 0x7f, v19
	v_mul_f32_e32 v20, 0.15915494, v20
	v_sin_f32_e32 v20, v20
	v_cvt_f32_ubyte0_e32 v21, v19
	v_add_u32_e32 v19, v19, v18
	v_mul_f32_e32 v21, 0x3d490fdb, v21
	v_and_b32_e32 v19, 0x7f, v19
	v_mul_f32_e32 v21, 0.15915494, v21
	v_sin_f32_e32 v21, v21
	v_cvt_f32_ubyte0_e32 v22, v19
	v_add_u32_e32 v19, v19, v18
	v_mul_f32_e32 v22, 0x3d490fdb, v22
	v_and_b32_e32 v19, 0x7f, v19
	v_mul_f32_e32 v22, 0.15915494, v22
	v_sin_f32_e32 v22, v22
	s_waitcnt vmcnt(63)
	v_fmac_f32_e32 v4, v84, v20
	v_cvt_f32_ubyte0_e32 v23, v19
	v_add_u32_e32 v19, v19, v18
	v_mul_f32_e32 v23, 0x3d490fdb, v23
	v_and_b32_e32 v19, 0x7f, v19
	v_mul_f32_e32 v23, 0.15915494, v23
	v_sin_f32_e32 v23, v23
	v_fmac_f32_e32 v4, v85, v21
	v_cvt_f32_ubyte0_e32 v20, v19
	v_add_u32_e32 v19, v19, v18
	v_mul_f32_e32 v20, 0x3d490fdb, v20
	v_and_b32_e32 v19, 0x7f, v19
	v_mul_f32_e32 v20, 0.15915494, v20
	v_sin_f32_e32 v20, v20
	v_fmac_f32_e32 v4, v86, v22
	v_cvt_f32_ubyte0_e32 v21, v19
	v_add_u32_e32 v19, v19, v18
	v_mul_f32_e32 v21, 0x3d490fdb, v21
	v_and_b32_e32 v19, 0x7f, v19
	v_mul_f32_e32 v21, 0.15915494, v21
	v_sin_f32_e32 v21, v21
	v_fmac_f32_e32 v4, v87, v23
	v_cvt_f32_ubyte0_e32 v22, v19
	v_add_u32_e32 v19, v19, v18
	v_mul_f32_e32 v22, 0x3d490fdb, v22
	v_and_b32_e32 v19, 0x7f, v19
	v_mul_f32_e32 v22, 0.15915494, v22
	v_sin_f32_e32 v22, v22
	v_fmac_f32_e32 v4, v88, v20
	v_cvt_f32_ubyte0_e32 v23, v19
	v_add_u32_e32 v19, v19, v18
	v_mul_f32_e32 v23, 0x3d490fdb, v23
	v_and_b32_e32 v19, 0x7f, v19
	v_mul_f32_e32 v23, 0.15915494, v23
	v_sin_f32_e32 v23, v23
	v_fmac_f32_e32 v4, v89, v21
	v_cvt_f32_ubyte0_e32 v20, v19
	v_add_u32_e32 v19, v19, v18
	v_mul_f32_e32 v20, 0x3d490fdb, v20
	v_and_b32_e32 v19, 0x7f, v19
	v_mul_f32_e32 v20, 0.15915494, v20
	v_sin_f32_e32 v20, v20
	v_fmac_f32_e32 v4, v90, v22
	v_cvt_f32_ubyte0_e32 v21, v19
	v_add_u32_e32 v19, v19, v18
	v_mul_f32_e32 v21, 0x3d490fdb, v21
	v_and_b32_e32 v19, 0x7f, v19
	v_mul_f32_e32 v21, 0.15915494, v21
	v_sin_f32_e32 v21, v21
	v_fmac_f32_e32 v4, v91, v23
	v_cvt_f32_ubyte0_e32 v22, v19
	v_add_u32_e32 v19, v19, v18
	v_mul_f32_e32 v22, 0x3d490fdb, v22
	v_and_b32_e32 v19, 0x7f, v19
	v_mul_f32_e32 v22, 0.15915494, v22
	v_sin_f32_e32 v22, v22
	v_fmac_f32_e32 v4, v92, v20
	v_cvt_f32_ubyte0_e32 v23, v19
	v_add_u32_e32 v19, v19, v18
	v_mul_f32_e32 v23, 0x3d490fdb, v23
	v_and_b32_e32 v19, 0x7f, v19
	v_mul_f32_e32 v23, 0.15915494, v23
	v_sin_f32_e32 v23, v23
	v_fmac_f32_e32 v4, v93, v21
	v_cvt_f32_ubyte0_e32 v20, v19
	v_add_u32_e32 v19, v19, v18
	v_mul_f32_e32 v20, 0x3d490fdb, v20
	v_and_b32_e32 v19, 0x7f, v19
	v_mul_f32_e32 v20, 0.15915494, v20
	v_sin_f32_e32 v20, v20
	v_fmac_f32_e32 v4, v94, v22
	v_cvt_f32_ubyte0_e32 v21, v19
	v_add_u32_e32 v19, v19, v18
	v_mul_f32_e32 v21, 0x3d490fdb, v21
	v_and_b32_e32 v19, 0x7f, v19
	v_mul_f32_e32 v21, 0.15915494, v21
	v_sin_f32_e32 v21, v21
	v_fmac_f32_e32 v4, v95, v23
	v_cvt_f32_ubyte0_e32 v22, v19
	v_add_u32_e32 v19, v19, v18
	v_mul_f32_e32 v22, 0x3d490fdb, v22
	v_and_b32_e32 v19, 0x7f, v19
	v_mul_f32_e32 v22, 0.15915494, v22
	v_sin_f32_e32 v22, v22
	v_fmac_f32_e32 v4, v96, v20
	v_cvt_f32_ubyte0_e32 v23, v19
	v_add_u32_e32 v19, v19, v18
	v_mul_f32_e32 v23, 0x3d490fdb, v23
	v_and_b32_e32 v19, 0x7f, v19
	v_mul_f32_e32 v23, 0.15915494, v23
	v_sin_f32_e32 v23, v23
	v_fmac_f32_e32 v4, v97, v21
	v_cvt_f32_ubyte0_e32 v20, v19
	v_add_u32_e32 v19, v19, v18
	v_mul_f32_e32 v20, 0x3d490fdb, v20
	v_and_b32_e32 v19, 0x7f, v19
	v_mul_f32_e32 v20, 0.15915494, v20
	v_sin_f32_e32 v20, v20
	v_fmac_f32_e32 v4, v98, v22
	v_cvt_f32_ubyte0_e32 v21, v19
	v_add_u32_e32 v19, v19, v18
	v_mul_f32_e32 v21, 0x3d490fdb, v21
	v_and_b32_e32 v19, 0x7f, v19
	v_mul_f32_e32 v21, 0.15915494, v21
	v_sin_f32_e32 v21, v21
	v_fmac_f32_e32 v4, v99, v23
	v_cvt_f32_ubyte0_e32 v22, v19
	v_add_u32_e32 v19, v19, v18
	v_mul_f32_e32 v22, 0x3d490fdb, v22
	v_and_b32_e32 v19, 0x7f, v19
	v_mul_f32_e32 v22, 0.15915494, v22
	v_sin_f32_e32 v22, v22
	v_fmac_f32_e32 v4, v100, v20
	v_cvt_f32_ubyte0_e32 v23, v19
	v_add_u32_e32 v19, v19, v18
	v_mul_f32_e32 v23, 0x3d490fdb, v23
	v_and_b32_e32 v19, 0x7f, v19
	v_mul_f32_e32 v23, 0.15915494, v23
	v_sin_f32_e32 v23, v23
	v_fmac_f32_e32 v4, v101, v21
	v_cvt_f32_ubyte0_e32 v20, v19
	v_add_u32_e32 v19, v19, v18
	v_mul_f32_e32 v20, 0x3d490fdb, v20
	v_and_b32_e32 v19, 0x7f, v19
	v_mul_f32_e32 v20, 0.15915494, v20
	v_sin_f32_e32 v20, v20
	v_fmac_f32_e32 v4, v102, v22
	v_cvt_f32_ubyte0_e32 v21, v19
	v_add_u32_e32 v19, v19, v18
	v_mul_f32_e32 v21, 0x3d490fdb, v21
	v_and_b32_e32 v19, 0x7f, v19
	v_mul_f32_e32 v21, 0.15915494, v21
	v_sin_f32_e32 v21, v21
	v_fmac_f32_e32 v4, v103, v23
	v_cvt_f32_ubyte0_e32 v22, v19
	v_add_u32_e32 v19, v19, v18
	v_mul_f32_e32 v22, 0x3d490fdb, v22
	v_and_b32_e32 v19, 0x7f, v19
	v_mul_f32_e32 v22, 0.15915494, v22
	v_sin_f32_e32 v22, v22
	v_fmac_f32_e32 v4, v104, v20
	v_cvt_f32_ubyte0_e32 v23, v19
	v_add_u32_e32 v19, v19, v18
	v_mul_f32_e32 v23, 0x3d490fdb, v23
	v_and_b32_e32 v19, 0x7f, v19
	v_mul_f32_e32 v23, 0.15915494, v23
	v_sin_f32_e32 v23, v23
	v_fmac_f32_e32 v4, v105, v21
	v_cvt_f32_ubyte0_e32 v20, v19
	v_add_u32_e32 v19, v19, v18
	v_mul_f32_e32 v20, 0x3d490fdb, v20
	v_and_b32_e32 v19, 0x7f, v19
	v_mul_f32_e32 v20, 0.15915494, v20
	v_sin_f32_e32 v20, v20
	v_fmac_f32_e32 v4, v106, v22
	v_cvt_f32_ubyte0_e32 v21, v19
	v_add_u32_e32 v19, v19, v18
	v_mul_f32_e32 v21, 0x3d490fdb, v21
	v_and_b32_e32 v19, 0x7f, v19
	v_mul_f32_e32 v21, 0.15915494, v21
	v_sin_f32_e32 v21, v21
	v_fmac_f32_e32 v4, v107, v23
	v_cvt_f32_ubyte0_e32 v22, v19
	v_add_u32_e32 v19, v19, v18
	v_mul_f32_e32 v22, 0x3d490fdb, v22
	v_and_b32_e32 v19, 0x7f, v19
	v_mul_f32_e32 v22, 0.15915494, v22
	v_sin_f32_e32 v22, v22
	v_fmac_f32_e32 v4, v108, v20
	v_cvt_f32_ubyte0_e32 v23, v19
	v_add_u32_e32 v19, v19, v18
	v_mul_f32_e32 v23, 0x3d490fdb, v23
	v_and_b32_e32 v19, 0x7f, v19
	v_mul_f32_e32 v23, 0.15915494, v23
	v_sin_f32_e32 v23, v23
	v_fmac_f32_e32 v4, v109, v21
	v_cvt_f32_ubyte0_e32 v20, v19
	v_add_u32_e32 v19, v19, v18
	v_mul_f32_e32 v20, 0x3d490fdb, v20
	v_and_b32_e32 v19, 0x7f, v19
	v_mul_f32_e32 v20, 0.15915494, v20
	v_sin_f32_e32 v20, v20
	v_fmac_f32_e32 v4, v110, v22
	v_cvt_f32_ubyte0_e32 v21, v19
	v_add_u32_e32 v19, v19, v18
	v_mul_f32_e32 v21, 0x3d490fdb, v21
	v_and_b32_e32 v19, 0x7f, v19
	v_mul_f32_e32 v21, 0.15915494, v21
	v_sin_f32_e32 v21, v21
	v_fmac_f32_e32 v4, v111, v23
	v_cvt_f32_ubyte0_e32 v22, v19
	v_add_u32_e32 v19, v19, v18
	v_mul_f32_e32 v22, 0x3d490fdb, v22
	v_and_b32_e32 v19, 0x7f, v19
	v_mul_f32_e32 v22, 0.15915494, v22
	v_sin_f32_e32 v22, v22
	v_fmac_f32_e32 v4, v112, v20
	v_cvt_f32_ubyte0_e32 v23, v19
	v_add_u32_e32 v19, v19, v18
	v_mul_f32_e32 v23, 0x3d490fdb, v23
	v_and_b32_e32 v19, 0x7f, v19
	v_mul_f32_e32 v23, 0.15915494, v23
	v_sin_f32_e32 v23, v23
	v_fmac_f32_e32 v4, v113, v21
	v_cvt_f32_ubyte0_e32 v20, v19
	v_add_u32_e32 v19, v19, v18
	v_mul_f32_e32 v20, 0x3d490fdb, v20
	v_and_b32_e32 v19, 0x7f, v19
	v_mul_f32_e32 v20, 0.15915494, v20
	v_sin_f32_e32 v20, v20
	v_fmac_f32_e32 v4, v114, v22
	v_cvt_f32_ubyte0_e32 v21, v19
	v_add_u32_e32 v19, v19, v18
	v_mul_f32_e32 v21, 0x3d490fdb, v21
	v_and_b32_e32 v19, 0x7f, v19
	v_mul_f32_e32 v21, 0.15915494, v21
	v_sin_f32_e32 v21, v21
	v_fmac_f32_e32 v4, v115, v23
	v_cvt_f32_ubyte0_e32 v22, v19
	v_add_u32_e32 v19, v19, v18
	v_mul_f32_e32 v22, 0x3d490fdb, v22
	v_and_b32_e32 v19, 0x7f, v19
	v_mul_f32_e32 v22, 0.15915494, v22
	v_sin_f32_e32 v22, v22
	v_fmac_f32_e32 v4, v116, v20
	v_cvt_f32_ubyte0_e32 v23, v19
	v_add_u32_e32 v19, v19, v18
	v_mul_f32_e32 v23, 0x3d490fdb, v23
	v_and_b32_e32 v19, 0x7f, v19
	v_mul_f32_e32 v23, 0.15915494, v23
	v_sin_f32_e32 v23, v23
	v_fmac_f32_e32 v4, v117, v21
	v_cvt_f32_ubyte0_e32 v20, v19
	v_add_u32_e32 v19, v19, v18
	v_mul_f32_e32 v20, 0x3d490fdb, v20
	v_and_b32_e32 v19, 0x7f, v19
	v_mul_f32_e32 v20, 0.15915494, v20
	v_sin_f32_e32 v20, v20
	v_fmac_f32_e32 v4, v118, v22
	v_cvt_f32_ubyte0_e32 v21, v19
	v_add_u32_e32 v19, v19, v18
	v_mul_f32_e32 v21, 0x3d490fdb, v21
	v_and_b32_e32 v19, 0x7f, v19
	v_mul_f32_e32 v21, 0.15915494, v21
	v_sin_f32_e32 v21, v21
	v_fmac_f32_e32 v4, v119, v23
	v_cvt_f32_ubyte0_e32 v22, v19
	v_add_u32_e32 v19, v19, v18
	v_mul_f32_e32 v22, 0x3d490fdb, v22
	v_and_b32_e32 v19, 0x7f, v19
	v_mul_f32_e32 v22, 0.15915494, v22
	v_sin_f32_e32 v22, v22
	v_fmac_f32_e32 v4, v120, v20
	v_cvt_f32_ubyte0_e32 v23, v19
	v_add_u32_e32 v19, v19, v18
	v_mul_f32_e32 v23, 0x3d490fdb, v23
	v_and_b32_e32 v19, 0x7f, v19
	v_mul_f32_e32 v23, 0.15915494, v23
	v_sin_f32_e32 v23, v23
	v_fmac_f32_e32 v4, v121, v21
	v_cvt_f32_ubyte0_e32 v20, v19
	v_add_u32_e32 v19, v19, v18
	v_mul_f32_e32 v20, 0x3d490fdb, v20
	v_and_b32_e32 v19, 0x7f, v19
	v_mul_f32_e32 v20, 0.15915494, v20
	v_sin_f32_e32 v20, v20
	v_fmac_f32_e32 v4, v122, v22
	v_cvt_f32_ubyte0_e32 v21, v19
	v_add_u32_e32 v19, v19, v18
	v_mul_f32_e32 v21, 0x3d490fdb, v21
	v_and_b32_e32 v19, 0x7f, v19
	v_mul_f32_e32 v21, 0.15915494, v21
	v_sin_f32_e32 v21, v21
	v_fmac_f32_e32 v4, v123, v23
	v_cvt_f32_ubyte0_e32 v22, v19
	v_add_u32_e32 v19, v19, v18
	v_mul_f32_e32 v22, 0x3d490fdb, v22
	v_and_b32_e32 v19, 0x7f, v19
	v_mul_f32_e32 v22, 0.15915494, v22
	v_sin_f32_e32 v22, v22
	v_fmac_f32_e32 v4, v124, v20
	v_cvt_f32_ubyte0_e32 v23, v19
	v_add_u32_e32 v19, v19, v18
	v_mul_f32_e32 v23, 0x3d490fdb, v23
	v_and_b32_e32 v19, 0x7f, v19
	v_mul_f32_e32 v23, 0.15915494, v23
	v_sin_f32_e32 v23, v23
	v_fmac_f32_e32 v4, v125, v21
	v_cvt_f32_ubyte0_e32 v20, v19
	v_add_u32_e32 v19, v19, v18
	v_mul_f32_e32 v20, 0x3d490fdb, v20
	v_and_b32_e32 v19, 0x7f, v19
	v_mul_f32_e32 v20, 0.15915494, v20
	v_sin_f32_e32 v20, v20
	v_fmac_f32_e32 v4, v126, v22
	v_cvt_f32_ubyte0_e32 v21, v19
	v_add_u32_e32 v19, v19, v18
	v_mul_f32_e32 v21, 0x3d490fdb, v21
	v_and_b32_e32 v19, 0x7f, v19
	v_mul_f32_e32 v21, 0.15915494, v21
	v_sin_f32_e32 v21, v21
	v_fmac_f32_e32 v4, v127, v23
	v_cvt_f32_ubyte0_e32 v22, v19
	v_add_u32_e32 v19, v19, v18
	v_mul_f32_e32 v22, 0x3d490fdb, v22
	v_and_b32_e32 v19, 0x7f, v19
	v_mul_f32_e32 v22, 0.15915494, v22
	v_sin_f32_e32 v22, v22
	v_fmac_f32_e32 v4, v128, v20
	v_cvt_f32_ubyte0_e32 v23, v19
	v_add_u32_e32 v19, v19, v18
	v_mul_f32_e32 v23, 0x3d490fdb, v23
	v_and_b32_e32 v19, 0x7f, v19
	v_mul_f32_e32 v23, 0.15915494, v23
	v_sin_f32_e32 v23, v23
	v_fmac_f32_e32 v4, v129, v21
	v_cvt_f32_ubyte0_e32 v20, v19
	v_add_u32_e32 v19, v19, v18
	v_mul_f32_e32 v20, 0x3d490fdb, v20
	v_and_b32_e32 v19, 0x7f, v19
	v_mul_f32_e32 v20, 0.15915494, v20
	v_sin_f32_e32 v20, v20
	v_fmac_f32_e32 v4, v130, v22
	v_cvt_f32_ubyte0_e32 v21, v19
	v_add_u32_e32 v19, v19, v18
	v_mul_f32_e32 v21, 0x3d490fdb, v21
	v_and_b32_e32 v19, 0x7f, v19
	v_mul_f32_e32 v21, 0.15915494, v21
	v_sin_f32_e32 v21, v21
	v_fmac_f32_e32 v4, v131, v23
	v_cvt_f32_ubyte0_e32 v22, v19
	v_add_u32_e32 v19, v19, v18
	v_mul_f32_e32 v22, 0x3d490fdb, v22
	v_and_b32_e32 v19, 0x7f, v19
	v_mul_f32_e32 v22, 0.15915494, v22
	v_sin_f32_e32 v22, v22
	v_fmac_f32_e32 v4, v132, v20
	v_cvt_f32_ubyte0_e32 v23, v19
	v_add_u32_e32 v19, v19, v18
	v_mul_f32_e32 v23, 0x3d490fdb, v23
	v_and_b32_e32 v19, 0x7f, v19
	v_mul_f32_e32 v23, 0.15915494, v23
	v_sin_f32_e32 v23, v23
	v_fmac_f32_e32 v4, v133, v21
	v_cvt_f32_ubyte0_e32 v20, v19
	v_add_u32_e32 v19, v19, v18
	v_mul_f32_e32 v20, 0x3d490fdb, v20
	v_and_b32_e32 v19, 0x7f, v19
	v_mul_f32_e32 v20, 0.15915494, v20
	v_sin_f32_e32 v20, v20
	v_fmac_f32_e32 v4, v134, v22
	v_cvt_f32_ubyte0_e32 v21, v19
	v_add_u32_e32 v19, v19, v18
	v_mul_f32_e32 v21, 0x3d490fdb, v21
	v_and_b32_e32 v19, 0x7f, v19
	v_mul_f32_e32 v21, 0.15915494, v21
	v_sin_f32_e32 v21, v21
	v_fmac_f32_e32 v4, v135, v23
	v_cvt_f32_ubyte0_e32 v22, v19
	v_add_u32_e32 v19, v19, v18
	v_mul_f32_e32 v22, 0x3d490fdb, v22
	v_and_b32_e32 v19, 0x7f, v19
	v_mul_f32_e32 v22, 0.15915494, v22
	v_sin_f32_e32 v22, v22
	v_fmac_f32_e32 v4, v136, v20
	v_cvt_f32_ubyte0_e32 v23, v19
	v_add_u32_e32 v19, v19, v18
	v_mul_f32_e32 v23, 0x3d490fdb, v23
	v_and_b32_e32 v19, 0x7f, v19
	v_mul_f32_e32 v23, 0.15915494, v23
	v_sin_f32_e32 v23, v23
	v_fmac_f32_e32 v4, v137, v21
	v_cvt_f32_ubyte0_e32 v20, v19
	v_add_u32_e32 v19, v19, v18
	v_mul_f32_e32 v20, 0x3d490fdb, v20
	v_and_b32_e32 v19, 0x7f, v19
	v_mul_f32_e32 v20, 0.15915494, v20
	v_sin_f32_e32 v20, v20
	v_fmac_f32_e32 v4, v138, v22
	v_cvt_f32_ubyte0_e32 v21, v19
	v_add_u32_e32 v19, v19, v18
	v_mul_f32_e32 v21, 0x3d490fdb, v21
	v_and_b32_e32 v19, 0x7f, v19
	v_mul_f32_e32 v21, 0.15915494, v21
	v_sin_f32_e32 v21, v21
	v_fmac_f32_e32 v4, v139, v23
	v_cvt_f32_ubyte0_e32 v22, v19
	v_add_u32_e32 v19, v19, v18
	v_mul_f32_e32 v22, 0x3d490fdb, v22
	v_and_b32_e32 v19, 0x7f, v19
	v_mul_f32_e32 v22, 0.15915494, v22
	v_sin_f32_e32 v22, v22
	v_fmac_f32_e32 v4, v140, v20
	v_cvt_f32_ubyte0_e32 v23, v19
	v_add_u32_e32 v19, v19, v18
	v_mul_f32_e32 v23, 0x3d490fdb, v23
	v_and_b32_e32 v19, 0x7f, v19
	v_mul_f32_e32 v23, 0.15915494, v23
	v_sin_f32_e32 v23, v23
	v_fmac_f32_e32 v4, v141, v21
	v_cvt_f32_ubyte0_e32 v20, v19
	v_add_u32_e32 v19, v19, v18
	v_mul_f32_e32 v20, 0x3d490fdb, v20
	v_and_b32_e32 v19, 0x7f, v19
	v_mul_f32_e32 v20, 0.15915494, v20
	v_sin_f32_e32 v20, v20
	v_fmac_f32_e32 v4, v142, v22
	v_cvt_f32_ubyte0_e32 v21, v19
	v_add_u32_e32 v19, v19, v18
	v_mul_f32_e32 v21, 0x3d490fdb, v21
	v_and_b32_e32 v19, 0x7f, v19
	v_mul_f32_e32 v21, 0.15915494, v21
	v_sin_f32_e32 v21, v21
	v_fmac_f32_e32 v4, v143, v23
	v_cvt_f32_ubyte0_e32 v22, v19
	v_add_u32_e32 v19, v19, v18
	v_mul_f32_e32 v22, 0x3d490fdb, v22
	v_and_b32_e32 v19, 0x7f, v19
	v_mul_f32_e32 v22, 0.15915494, v22
	v_sin_f32_e32 v22, v22
	v_fmac_f32_e32 v4, v144, v20
	v_cvt_f32_ubyte0_e32 v23, v19
	v_add_u32_e32 v19, v19, v18
	v_mul_f32_e32 v23, 0x3d490fdb, v23
	v_and_b32_e32 v19, 0x7f, v19
	v_mul_f32_e32 v23, 0.15915494, v23
	v_sin_f32_e32 v23, v23
	v_fmac_f32_e32 v4, v145, v21
	v_cvt_f32_ubyte0_e32 v20, v19
	v_add_u32_e32 v19, v19, v18
	v_mul_f32_e32 v20, 0x3d490fdb, v20
	v_and_b32_e32 v19, 0x7f, v19
	v_mul_f32_e32 v20, 0.15915494, v20
	v_sin_f32_e32 v20, v20
	v_fmac_f32_e32 v4, v146, v22
	v_cvt_f32_ubyte0_e32 v21, v19
	v_add_u32_e32 v19, v19, v18
	v_mul_f32_e32 v21, 0x3d490fdb, v21
	v_and_b32_e32 v19, 0x7f, v19
	v_mul_f32_e32 v21, 0.15915494, v21
	v_sin_f32_e32 v21, v21
	v_fmac_f32_e32 v4, v147, v23
	v_cvt_f32_ubyte0_e32 v22, v19
	v_add_u32_e32 v19, v19, v18
	v_mul_f32_e32 v22, 0x3d490fdb, v22
	v_and_b32_e32 v19, 0x7f, v19
	v_mul_f32_e32 v22, 0.15915494, v22
	v_sin_f32_e32 v22, v22
	s_waitcnt vmcnt(63)
	v_fmac_f32_e32 v4, v148, v20
	v_cvt_f32_ubyte0_e32 v23, v19
	v_add_u32_e32 v19, v19, v18
	v_mul_f32_e32 v23, 0x3d490fdb, v23
	v_and_b32_e32 v19, 0x7f, v19
	v_mul_f32_e32 v23, 0.15915494, v23
	v_sin_f32_e32 v23, v23
	s_waitcnt vmcnt(62)
	v_fmac_f32_e32 v4, v149, v21
	v_cvt_f32_ubyte0_e32 v20, v19
	v_add_u32_e32 v19, v19, v18
	v_mul_f32_e32 v20, 0x3d490fdb, v20
	v_and_b32_e32 v19, 0x7f, v19
	v_mul_f32_e32 v20, 0.15915494, v20
	v_sin_f32_e32 v20, v20
	s_waitcnt vmcnt(61)
	v_fmac_f32_e32 v4, v150, v22
	v_cvt_f32_ubyte0_e32 v21, v19
	v_add_u32_e32 v19, v19, v18
	v_mul_f32_e32 v21, 0x3d490fdb, v21
	v_and_b32_e32 v19, 0x7f, v19
	v_mul_f32_e32 v21, 0.15915494, v21
	v_sin_f32_e32 v21, v21
	s_waitcnt vmcnt(60)
	v_fmac_f32_e32 v4, v151, v23
	v_cvt_f32_ubyte0_e32 v22, v19
	v_add_u32_e32 v19, v19, v18
	v_mul_f32_e32 v22, 0x3d490fdb, v22
	v_and_b32_e32 v19, 0x7f, v19
	v_mul_f32_e32 v22, 0.15915494, v22
	v_sin_f32_e32 v22, v22
	s_waitcnt vmcnt(59)
	v_fmac_f32_e32 v4, v152, v20
	v_cvt_f32_ubyte0_e32 v23, v19
	v_add_u32_e32 v19, v19, v18
	v_mul_f32_e32 v23, 0x3d490fdb, v23
	v_and_b32_e32 v19, 0x7f, v19
	v_mul_f32_e32 v23, 0.15915494, v23
	v_sin_f32_e32 v23, v23
	s_waitcnt vmcnt(58)
	v_fmac_f32_e32 v4, v153, v21
	v_cvt_f32_ubyte0_e32 v20, v19
	v_add_u32_e32 v19, v19, v18
	v_mul_f32_e32 v20, 0x3d490fdb, v20
	v_and_b32_e32 v19, 0x7f, v19
	v_mul_f32_e32 v20, 0.15915494, v20
	v_sin_f32_e32 v20, v20
	s_waitcnt vmcnt(57)
	v_fmac_f32_e32 v4, v154, v22
	v_cvt_f32_ubyte0_e32 v21, v19
	v_add_u32_e32 v19, v19, v18
	v_mul_f32_e32 v21, 0x3d490fdb, v21
	v_and_b32_e32 v19, 0x7f, v19
	v_mul_f32_e32 v21, 0.15915494, v21
	v_sin_f32_e32 v21, v21
	s_waitcnt vmcnt(56)
	v_fmac_f32_e32 v4, v155, v23
	v_cvt_f32_ubyte0_e32 v22, v19
	v_add_u32_e32 v19, v19, v18
	v_mul_f32_e32 v22, 0x3d490fdb, v22
	v_and_b32_e32 v19, 0x7f, v19
	v_mul_f32_e32 v22, 0.15915494, v22
	v_sin_f32_e32 v22, v22
	s_waitcnt vmcnt(55)
	v_fmac_f32_e32 v4, v156, v20
	v_cvt_f32_ubyte0_e32 v23, v19
	v_add_u32_e32 v19, v19, v18
	v_mul_f32_e32 v23, 0x3d490fdb, v23
	v_and_b32_e32 v19, 0x7f, v19
	v_mul_f32_e32 v23, 0.15915494, v23
	v_sin_f32_e32 v23, v23
	s_waitcnt vmcnt(54)
	v_fmac_f32_e32 v4, v157, v21
	v_cvt_f32_ubyte0_e32 v20, v19
	v_add_u32_e32 v19, v19, v18
	v_mul_f32_e32 v20, 0x3d490fdb, v20
	v_and_b32_e32 v19, 0x7f, v19
	v_mul_f32_e32 v20, 0.15915494, v20
	v_sin_f32_e32 v20, v20
	s_waitcnt vmcnt(53)
	v_fmac_f32_e32 v4, v158, v22
	v_cvt_f32_ubyte0_e32 v21, v19
	v_add_u32_e32 v19, v19, v18
	v_mul_f32_e32 v21, 0x3d490fdb, v21
	v_and_b32_e32 v19, 0x7f, v19
	v_mul_f32_e32 v21, 0.15915494, v21
	v_sin_f32_e32 v21, v21
	s_waitcnt vmcnt(52)
	v_fmac_f32_e32 v4, v159, v23
	v_cvt_f32_ubyte0_e32 v22, v19
	v_add_u32_e32 v19, v19, v18
	v_mul_f32_e32 v22, 0x3d490fdb, v22
	v_and_b32_e32 v19, 0x7f, v19
	v_mul_f32_e32 v22, 0.15915494, v22
	v_sin_f32_e32 v22, v22
	s_waitcnt vmcnt(51)
	v_fmac_f32_e32 v4, v160, v20
	v_cvt_f32_ubyte0_e32 v23, v19
	v_add_u32_e32 v19, v19, v18
	v_mul_f32_e32 v23, 0x3d490fdb, v23
	v_and_b32_e32 v19, 0x7f, v19
	v_mul_f32_e32 v23, 0.15915494, v23
	v_sin_f32_e32 v23, v23
	s_waitcnt vmcnt(50)
	v_fmac_f32_e32 v4, v161, v21
	v_cvt_f32_ubyte0_e32 v20, v19
	v_add_u32_e32 v19, v19, v18
	v_mul_f32_e32 v20, 0x3d490fdb, v20
	v_and_b32_e32 v19, 0x7f, v19
	v_mul_f32_e32 v20, 0.15915494, v20
	v_sin_f32_e32 v20, v20
	s_waitcnt vmcnt(49)
	v_fmac_f32_e32 v4, v162, v22
	v_cvt_f32_ubyte0_e32 v21, v19
	v_add_u32_e32 v19, v19, v18
	v_mul_f32_e32 v21, 0x3d490fdb, v21
	v_and_b32_e32 v19, 0x7f, v19
	v_mul_f32_e32 v21, 0.15915494, v21
	v_sin_f32_e32 v21, v21
	s_waitcnt vmcnt(48)
	v_fmac_f32_e32 v4, v163, v23
	v_cvt_f32_ubyte0_e32 v22, v19
	v_add_u32_e32 v19, v19, v18
	v_mul_f32_e32 v22, 0x3d490fdb, v22
	v_and_b32_e32 v19, 0x7f, v19
	v_mul_f32_e32 v22, 0.15915494, v22
	v_sin_f32_e32 v22, v22
	s_waitcnt vmcnt(47)
	v_fmac_f32_e32 v4, v164, v20
	v_cvt_f32_ubyte0_e32 v23, v19
	v_add_u32_e32 v19, v19, v18
	v_mul_f32_e32 v23, 0x3d490fdb, v23
	v_and_b32_e32 v19, 0x7f, v19
	v_mul_f32_e32 v23, 0.15915494, v23
	v_sin_f32_e32 v23, v23
	s_waitcnt vmcnt(46)
	v_fmac_f32_e32 v4, v165, v21
	v_cvt_f32_ubyte0_e32 v20, v19
	v_add_u32_e32 v19, v19, v18
	v_mul_f32_e32 v20, 0x3d490fdb, v20
	v_and_b32_e32 v19, 0x7f, v19
	v_mul_f32_e32 v20, 0.15915494, v20
	v_sin_f32_e32 v20, v20
	s_waitcnt vmcnt(45)
	v_fmac_f32_e32 v4, v166, v22
	v_cvt_f32_ubyte0_e32 v21, v19
	v_add_u32_e32 v19, v19, v18
	v_mul_f32_e32 v21, 0x3d490fdb, v21
	v_and_b32_e32 v19, 0x7f, v19
	v_mul_f32_e32 v21, 0.15915494, v21
	v_sin_f32_e32 v21, v21
	s_waitcnt vmcnt(44)
	v_fmac_f32_e32 v4, v167, v23
	v_cvt_f32_ubyte0_e32 v22, v19
	v_add_u32_e32 v19, v19, v18
	v_mul_f32_e32 v22, 0x3d490fdb, v22
	v_and_b32_e32 v19, 0x7f, v19
	v_mul_f32_e32 v22, 0.15915494, v22
	v_sin_f32_e32 v22, v22
	s_waitcnt vmcnt(43)
	v_fmac_f32_e32 v4, v168, v20
	v_cvt_f32_ubyte0_e32 v23, v19
	v_add_u32_e32 v19, v19, v18
	v_mul_f32_e32 v23, 0x3d490fdb, v23
	v_and_b32_e32 v19, 0x7f, v19
	v_mul_f32_e32 v23, 0.15915494, v23
	v_sin_f32_e32 v23, v23
	s_waitcnt vmcnt(42)
	v_fmac_f32_e32 v4, v169, v21
	v_cvt_f32_ubyte0_e32 v20, v19
	v_add_u32_e32 v19, v19, v18
	v_mul_f32_e32 v20, 0x3d490fdb, v20
	v_and_b32_e32 v19, 0x7f, v19
	v_mul_f32_e32 v20, 0.15915494, v20
	v_sin_f32_e32 v20, v20
	s_waitcnt vmcnt(41)
	v_fmac_f32_e32 v4, v170, v22
	v_cvt_f32_ubyte0_e32 v21, v19
	v_add_u32_e32 v19, v19, v18
	v_mul_f32_e32 v21, 0x3d490fdb, v21
	v_and_b32_e32 v19, 0x7f, v19
	v_mul_f32_e32 v21, 0.15915494, v21
	v_sin_f32_e32 v21, v21
	s_waitcnt vmcnt(40)
	v_fmac_f32_e32 v4, v171, v23
	v_cvt_f32_ubyte0_e32 v22, v19
	v_add_u32_e32 v19, v19, v18
	v_mul_f32_e32 v22, 0x3d490fdb, v22
	v_and_b32_e32 v19, 0x7f, v19
	v_mul_f32_e32 v22, 0.15915494, v22
	v_sin_f32_e32 v22, v22
	s_waitcnt vmcnt(39)
	v_fmac_f32_e32 v4, v172, v20
	v_cvt_f32_ubyte0_e32 v23, v19
	v_add_u32_e32 v19, v19, v18
	v_mul_f32_e32 v23, 0x3d490fdb, v23
	v_and_b32_e32 v19, 0x7f, v19
	v_mul_f32_e32 v23, 0.15915494, v23
	v_sin_f32_e32 v23, v23
	s_waitcnt vmcnt(38)
	v_fmac_f32_e32 v4, v173, v21
	v_cvt_f32_ubyte0_e32 v20, v19
	v_add_u32_e32 v19, v19, v18
	v_mul_f32_e32 v20, 0x3d490fdb, v20
	v_and_b32_e32 v19, 0x7f, v19
	v_mul_f32_e32 v20, 0.15915494, v20
	v_sin_f32_e32 v20, v20
	s_waitcnt vmcnt(37)
	v_fmac_f32_e32 v4, v174, v22
	v_cvt_f32_ubyte0_e32 v21, v19
	v_add_u32_e32 v19, v19, v18
	v_mul_f32_e32 v21, 0x3d490fdb, v21
	v_and_b32_e32 v19, 0x7f, v19
	v_mul_f32_e32 v21, 0.15915494, v21
	v_sin_f32_e32 v21, v21
	s_waitcnt vmcnt(36)
	v_fmac_f32_e32 v4, v175, v23
	v_cvt_f32_ubyte0_e32 v22, v19
	v_add_u32_e32 v19, v19, v18
	v_mul_f32_e32 v22, 0x3d490fdb, v22
	v_and_b32_e32 v19, 0x7f, v19
	v_mul_f32_e32 v22, 0.15915494, v22
	v_sin_f32_e32 v22, v22
	s_waitcnt vmcnt(35)
	v_fmac_f32_e32 v4, v178, v20
	v_cvt_f32_ubyte0_e32 v23, v19
	v_add_u32_e32 v19, v19, v18
	v_mul_f32_e32 v23, 0x3d490fdb, v23
	v_and_b32_e32 v19, 0x7f, v19
	v_mul_f32_e32 v23, 0.15915494, v23
	v_sin_f32_e32 v23, v23
	s_waitcnt vmcnt(34)
	v_fmac_f32_e32 v4, v179, v21
	v_cvt_f32_ubyte0_e32 v20, v19
	v_add_u32_e32 v19, v19, v18
	v_mul_f32_e32 v20, 0x3d490fdb, v20
	v_and_b32_e32 v19, 0x7f, v19
	v_mul_f32_e32 v20, 0.15915494, v20
	v_sin_f32_e32 v20, v20
	s_waitcnt vmcnt(33)
	v_fmac_f32_e32 v4, v180, v22
	v_cvt_f32_ubyte0_e32 v21, v19
	v_add_u32_e32 v19, v19, v18
	v_mul_f32_e32 v21, 0x3d490fdb, v21
	v_and_b32_e32 v19, 0x7f, v19
	v_mul_f32_e32 v21, 0.15915494, v21
	v_sin_f32_e32 v21, v21
	s_waitcnt vmcnt(32)
	v_fmac_f32_e32 v4, v181, v23
	v_cvt_f32_ubyte0_e32 v22, v19
	v_add_u32_e32 v19, v19, v18
	v_mul_f32_e32 v22, 0x3d490fdb, v22
	v_and_b32_e32 v19, 0x7f, v19
	v_mul_f32_e32 v22, 0.15915494, v22
	v_sin_f32_e32 v22, v22
	s_waitcnt vmcnt(31)
	v_fmac_f32_e32 v4, v182, v20
	v_cvt_f32_ubyte0_e32 v23, v19
	v_add_u32_e32 v19, v19, v18
	v_mul_f32_e32 v23, 0x3d490fdb, v23
	v_and_b32_e32 v19, 0x7f, v19
	v_mul_f32_e32 v23, 0.15915494, v23
	v_sin_f32_e32 v23, v23
	s_waitcnt vmcnt(30)
	v_fmac_f32_e32 v4, v183, v21
	v_cvt_f32_ubyte0_e32 v20, v19
	v_add_u32_e32 v19, v19, v18
	v_mul_f32_e32 v20, 0x3d490fdb, v20
	v_and_b32_e32 v19, 0x7f, v19
	v_mul_f32_e32 v20, 0.15915494, v20
	v_sin_f32_e32 v20, v20
	s_waitcnt vmcnt(29)
	v_fmac_f32_e32 v4, v184, v22
	v_cvt_f32_ubyte0_e32 v21, v19
	v_add_u32_e32 v19, v19, v18
	v_mul_f32_e32 v21, 0x3d490fdb, v21
	v_and_b32_e32 v19, 0x7f, v19
	v_mul_f32_e32 v21, 0.15915494, v21
	v_sin_f32_e32 v21, v21
	s_waitcnt vmcnt(28)
	v_fmac_f32_e32 v4, v185, v23
	v_cvt_f32_ubyte0_e32 v22, v19
	v_add_u32_e32 v19, v19, v18
	v_mul_f32_e32 v22, 0x3d490fdb, v22
	v_and_b32_e32 v19, 0x7f, v19
	v_mul_f32_e32 v22, 0.15915494, v22
	v_sin_f32_e32 v22, v22
	s_waitcnt vmcnt(27)
	v_fmac_f32_e32 v4, v186, v20
	v_cvt_f32_ubyte0_e32 v23, v19
	v_add_u32_e32 v19, v19, v18
	v_mul_f32_e32 v23, 0x3d490fdb, v23
	v_and_b32_e32 v19, 0x7f, v19
	v_mul_f32_e32 v23, 0.15915494, v23
	v_sin_f32_e32 v23, v23
	s_waitcnt vmcnt(26)
	v_fmac_f32_e32 v4, v187, v21
	v_cvt_f32_ubyte0_e32 v20, v19
	v_add_u32_e32 v19, v19, v18
	v_mul_f32_e32 v20, 0x3d490fdb, v20
	v_and_b32_e32 v19, 0x7f, v19
	v_mul_f32_e32 v20, 0.15915494, v20
	v_sin_f32_e32 v20, v20
	s_waitcnt vmcnt(25)
	v_fmac_f32_e32 v4, v188, v22
	v_cvt_f32_ubyte0_e32 v21, v19
	v_add_u32_e32 v19, v19, v18
	v_mul_f32_e32 v21, 0x3d490fdb, v21
	v_and_b32_e32 v19, 0x7f, v19
	v_mul_f32_e32 v21, 0.15915494, v21
	v_sin_f32_e32 v21, v21
	s_waitcnt vmcnt(24)
	v_fmac_f32_e32 v4, v189, v23
	v_cvt_f32_ubyte0_e32 v22, v19
	v_add_u32_e32 v19, v19, v18
	v_mul_f32_e32 v22, 0x3d490fdb, v22
	v_and_b32_e32 v19, 0x7f, v19
	v_mul_f32_e32 v22, 0.15915494, v22
	v_sin_f32_e32 v22, v22
	s_waitcnt vmcnt(23)
	v_fmac_f32_e32 v4, v190, v20
	v_cvt_f32_ubyte0_e32 v23, v19
	v_add_u32_e32 v19, v19, v18
	v_mul_f32_e32 v23, 0x3d490fdb, v23
	v_and_b32_e32 v19, 0x7f, v19
	v_mul_f32_e32 v23, 0.15915494, v23
	v_sin_f32_e32 v23, v23
	s_waitcnt vmcnt(22)
	v_fmac_f32_e32 v4, v191, v21
	v_cvt_f32_ubyte0_e32 v20, v19
	v_add_u32_e32 v19, v19, v18
	v_mul_f32_e32 v20, 0x3d490fdb, v20
	v_and_b32_e32 v19, 0x7f, v19
	v_mul_f32_e32 v20, 0.15915494, v20
	v_sin_f32_e32 v20, v20
	s_waitcnt vmcnt(21)
	v_fmac_f32_e32 v4, v192, v22
	v_cvt_f32_ubyte0_e32 v21, v19
	v_add_u32_e32 v19, v19, v18
	v_mul_f32_e32 v21, 0x3d490fdb, v21
	v_and_b32_e32 v19, 0x7f, v19
	v_mul_f32_e32 v21, 0.15915494, v21
	v_sin_f32_e32 v21, v21
	s_waitcnt vmcnt(20)
	v_fmac_f32_e32 v4, v193, v23
	v_cvt_f32_ubyte0_e32 v22, v19
	v_add_u32_e32 v19, v19, v18
	v_mul_f32_e32 v22, 0x3d490fdb, v22
	v_and_b32_e32 v19, 0x7f, v19
	v_mul_f32_e32 v22, 0.15915494, v22
	v_sin_f32_e32 v22, v22
	s_waitcnt vmcnt(19)
	v_fmac_f32_e32 v4, v194, v20
	v_cvt_f32_ubyte0_e32 v23, v19
	v_add_u32_e32 v19, v19, v18
	v_mul_f32_e32 v23, 0x3d490fdb, v23
	v_and_b32_e32 v19, 0x7f, v19
	v_mul_f32_e32 v23, 0.15915494, v23
	v_sin_f32_e32 v23, v23
	s_waitcnt vmcnt(18)
	v_fmac_f32_e32 v4, v195, v21
	v_cvt_f32_ubyte0_e32 v20, v19
	v_add_u32_e32 v19, v19, v18
	v_mul_f32_e32 v20, 0x3d490fdb, v20
	v_and_b32_e32 v19, 0x7f, v19
	v_mul_f32_e32 v20, 0.15915494, v20
	v_sin_f32_e32 v20, v20
	s_waitcnt vmcnt(17)
	v_fmac_f32_e32 v4, v196, v22
	v_cvt_f32_ubyte0_e32 v21, v19
	v_add_u32_e32 v19, v19, v18
	v_mul_f32_e32 v21, 0x3d490fdb, v21
	v_and_b32_e32 v19, 0x7f, v19
	v_mul_f32_e32 v21, 0.15915494, v21
	v_sin_f32_e32 v21, v21
	s_waitcnt vmcnt(16)
	v_fmac_f32_e32 v4, v197, v23
	v_cvt_f32_ubyte0_e32 v22, v19
	v_add_u32_e32 v19, v19, v18
	v_mul_f32_e32 v22, 0x3d490fdb, v22
	v_and_b32_e32 v19, 0x7f, v19
	v_mul_f32_e32 v22, 0.15915494, v22
	v_sin_f32_e32 v22, v22
	s_waitcnt vmcnt(15)
	v_fmac_f32_e32 v4, v198, v20
	v_cvt_f32_ubyte0_e32 v23, v19
	v_add_u32_e32 v19, v19, v18
	v_mul_f32_e32 v23, 0x3d490fdb, v23
	v_and_b32_e32 v19, 0x7f, v19
	v_mul_f32_e32 v23, 0.15915494, v23
	v_sin_f32_e32 v23, v23
	s_waitcnt vmcnt(14)
	v_fmac_f32_e32 v4, v199, v21
	v_cvt_f32_ubyte0_e32 v20, v19
	v_add_u32_e32 v19, v19, v18
	v_mul_f32_e32 v20, 0x3d490fdb, v20
	v_and_b32_e32 v19, 0x7f, v19
	v_mul_f32_e32 v20, 0.15915494, v20
	v_sin_f32_e32 v20, v20
	s_waitcnt vmcnt(13)
	v_fmac_f32_e32 v4, v200, v22
	v_cvt_f32_ubyte0_e32 v21, v19
	v_add_u32_e32 v19, v19, v18
	v_mul_f32_e32 v21, 0x3d490fdb, v21
	v_and_b32_e32 v19, 0x7f, v19
	v_mul_f32_e32 v21, 0.15915494, v21
	v_sin_f32_e32 v21, v21
	s_waitcnt vmcnt(12)
	v_fmac_f32_e32 v4, v201, v23
	v_cvt_f32_ubyte0_e32 v22, v19
	v_add_u32_e32 v19, v19, v18
	v_mul_f32_e32 v22, 0x3d490fdb, v22
	v_and_b32_e32 v19, 0x7f, v19
	v_mul_f32_e32 v22, 0.15915494, v22
	v_sin_f32_e32 v22, v22
	s_waitcnt vmcnt(11)
	v_fmac_f32_e32 v4, v202, v20
	v_cvt_f32_ubyte0_e32 v23, v19
	v_add_u32_e32 v19, v19, v18
	v_mul_f32_e32 v23, 0x3d490fdb, v23
	v_and_b32_e32 v19, 0x7f, v19
	v_mul_f32_e32 v23, 0.15915494, v23
	v_sin_f32_e32 v23, v23
	s_waitcnt vmcnt(10)
	v_fmac_f32_e32 v4, v203, v21
	v_cvt_f32_ubyte0_e32 v20, v19
	v_add_u32_e32 v19, v19, v18
	v_mul_f32_e32 v20, 0x3d490fdb, v20
	v_and_b32_e32 v19, 0x7f, v19
	v_mul_f32_e32 v20, 0.15915494, v20
	v_sin_f32_e32 v20, v20
	s_waitcnt vmcnt(9)
	v_fmac_f32_e32 v4, v204, v22
	v_cvt_f32_ubyte0_e32 v21, v19
	v_add_u32_e32 v19, v19, v18
	v_mul_f32_e32 v21, 0x3d490fdb, v21
	v_and_b32_e32 v19, 0x7f, v19
	v_mul_f32_e32 v21, 0.15915494, v21
	v_sin_f32_e32 v21, v21
	s_waitcnt vmcnt(8)
	v_fmac_f32_e32 v4, v205, v23
	v_cvt_f32_ubyte0_e32 v22, v19
	v_add_u32_e32 v19, v19, v18
	v_mul_f32_e32 v22, 0x3d490fdb, v22
	v_and_b32_e32 v19, 0x7f, v19
	v_mul_f32_e32 v22, 0.15915494, v22
	v_sin_f32_e32 v22, v22
	s_waitcnt vmcnt(7)
	v_fmac_f32_e32 v4, v206, v20
	v_cvt_f32_ubyte0_e32 v23, v19
	v_add_u32_e32 v19, v19, v18
	v_mul_f32_e32 v23, 0x3d490fdb, v23
	v_and_b32_e32 v19, 0x7f, v19
	v_mul_f32_e32 v23, 0.15915494, v23
	v_sin_f32_e32 v23, v23
	s_waitcnt vmcnt(6)
	v_fmac_f32_e32 v4, v207, v21
	v_cvt_f32_ubyte0_e32 v20, v19
	v_add_u32_e32 v19, v19, v18
	v_mul_f32_e32 v20, 0x3d490fdb, v20
	v_and_b32_e32 v19, 0x7f, v19
	v_mul_f32_e32 v20, 0.15915494, v20
	v_sin_f32_e32 v20, v20
	s_waitcnt vmcnt(5)
	v_fmac_f32_e32 v4, v208, v22
	v_cvt_f32_ubyte0_e32 v21, v19
	v_add_u32_e32 v19, v19, v18
	v_mul_f32_e32 v21, 0x3d490fdb, v21
	v_and_b32_e32 v19, 0x7f, v19
	v_mul_f32_e32 v21, 0.15915494, v21
	v_sin_f32_e32 v21, v21
	s_waitcnt vmcnt(4)
	v_fmac_f32_e32 v4, v209, v23
	v_cvt_f32_ubyte0_e32 v22, v19
	v_add_u32_e32 v19, v19, v18
	v_mul_f32_e32 v22, 0x3d490fdb, v22
	v_and_b32_e32 v19, 0x7f, v19
	v_mul_f32_e32 v22, 0.15915494, v22
	v_sin_f32_e32 v22, v22
	s_waitcnt vmcnt(3)
	v_fmac_f32_e32 v4, v210, v20
	v_cvt_f32_ubyte0_e32 v23, v19
	v_add_u32_e32 v19, v19, v18
	v_mul_f32_e32 v23, 0x3d490fdb, v23
	v_and_b32_e32 v19, 0x7f, v19
	v_mul_f32_e32 v23, 0.15915494, v23
	v_sin_f32_e32 v23, v23
	s_waitcnt vmcnt(2)
	v_fmac_f32_e32 v4, v211, v21
	s_waitcnt vmcnt(1)
	v_fmac_f32_e32 v4, v212, v22
	s_waitcnt vmcnt(0)
	v_fmac_f32_e32 v4, v213, v23
.Lmc_done:
	v_lshl_add_u64 v[6:7], v[0:1], 1, v[2:3]
	v_lshl_add_u64 v[0:1], v[0:1], 0, s[28:29]
	v_cmp_lt_u64_e32 vcc, s[12:13], v[0:1]
	v_cvt_pk_bf16_f32 v4, v4, s0
	v_add_u32_e32 v8, s3, v8
	v_add_u32_e32 v9, s16, v9
	v_add_u32_e32 v10, s17, v10
	v_add_u32_e32 v11, s18, v11
	v_add_u32_e32 v12, s19, v12
	v_add_u32_e32 v13, s20, v13
	s_or_b64 s[10:11], vcc, s[10:11]
	v_add_u32_e32 v14, s21, v14
	global_store_short v[6:7], v4, off
	s_andn2_b64 exec, exec, s[10:11]
	s_cbranch_execnz .LBB0_96
